# K-loops: counted lgkmcnt waits per MFMA instead of lgkmcnt(0) before the first MFMA of each compute segment
# speedup vs baseline: 1.0132x; 1.0093x over previous
.LBB0_119:
	s_add_u32 s26, s6, 0xfff80080
	s_addc_u32 s27, s7, -1
	s_add_i32 s66, 0, 0x10000
	v_add_u32_e32 v44, s66, v194
	ds_read_b128 v[24:27], v44
	ds_read_b128 v[32:35], v44 offset:1024
	ds_read_b128 v[40:43], v44 offset:2048
	ds_read_b128 v[44:47], v44 offset:3072
	s_cmp_eq_u32 s57, 28
	s_cselect_b32 s29, s25, s27
	s_cselect_b32 s28, s24, s26
	s_cselect_b32 s27, s9, s19
	s_cselect_b32 s26, s8, s11
	v_lshl_add_u64 v[180:181], s[6:7], 0, v[168:169]
	s_add_i32 m0, s36, 0xc000
	ds_read_b128 v[172:175], v196
	ds_read_b128 v[176:179], v196 offset:1024
	ds_read_b128 v[198:201], v196 offset:2048
	ds_read_b128 v[202:205], v196 offset:3072
	ds_read_b128 v[206:209], v196 offset:4096
	ds_read_b128 v[210:213], v196 offset:5120
	ds_read_b128 v[214:217], v196 offset:6144
	ds_read_b128 v[218:221], v196 offset:7168
	global_load_lds_dwordx4 v[180:181], off
	v_lshl_add_u64 v[180:181], s[6:7], 0, v[170:171]
	s_add_i32 m0, s36, 0xe000
	s_nop 0
	global_load_lds_dwordx4 v[180:181], off
	s_waitcnt lgkmcnt(8)
	s_barrier
	s_setprio 1
	s_waitcnt lgkmcnt(7)
	v_mfma_f32_16x16x32_bf16 v[140:143], v[24:27], v[172:175], v[140:143]
	v_mfma_f32_16x16x32_bf16 v[136:139], v[40:43], v[172:175], v[136:139]
	s_waitcnt lgkmcnt(5)
	v_mfma_f32_16x16x32_bf16 v[124:127], v[24:27], v[198:201], v[124:127]
	v_mfma_f32_16x16x32_bf16 v[120:123], v[40:43], v[198:201], v[120:123]
	s_waitcnt lgkmcnt(3)
	v_mfma_f32_16x16x32_bf16 v[108:111], v[24:27], v[206:209], v[108:111]
	v_mfma_f32_16x16x32_bf16 v[104:107], v[40:43], v[206:209], v[104:107]
	s_waitcnt lgkmcnt(1)
	v_mfma_f32_16x16x32_bf16 v[92:95], v[24:27], v[214:217], v[92:95]
	v_mfma_f32_16x16x32_bf16 v[88:91], v[40:43], v[214:217], v[88:91]
	v_mfma_f32_16x16x32_bf16 v[140:143], v[32:35], v[176:179], v[140:143]
	v_mfma_f32_16x16x32_bf16 v[136:139], v[44:47], v[176:179], v[136:139]
	v_mfma_f32_16x16x32_bf16 v[124:127], v[32:35], v[202:205], v[124:127]
	v_mfma_f32_16x16x32_bf16 v[120:123], v[44:47], v[202:205], v[120:123]
	v_mfma_f32_16x16x32_bf16 v[108:111], v[32:35], v[210:213], v[108:111]
	v_mfma_f32_16x16x32_bf16 v[104:107], v[44:47], v[210:213], v[104:107]
	s_waitcnt lgkmcnt(0)
	v_mfma_f32_16x16x32_bf16 v[92:95], v[32:35], v[218:221], v[92:95]
	v_mfma_f32_16x16x32_bf16 v[88:91], v[44:47], v[218:221], v[88:91]
	s_setprio 0
	s_barrier
	s_add_i32 s70, 0, 0x14000
	v_add_u32_e32 v180, s70, v194
	s_add_i32 s66, s66, s35
	ds_read_b128 v[222:225], v180
	ds_read_b128 v[226:229], v180 offset:1024
	ds_read_b128 v[230:233], v180 offset:2048
	ds_read_b128 v[234:237], v180 offset:3072
	v_lshl_add_u64 v[180:181], s[26:27], 0, v[144:145]
	s_mov_b32 m0, s66
	v_lshl_add_u64 v[238:239], s[26:27], 0, v[166:167]
	global_load_lds_dwordx4 v[180:181], off
	s_add_i32 m0, s66, 0x2000
	s_nop 0
	global_load_lds_dwordx4 v[238:239], off
	s_barrier
	s_setprio 1
	s_waitcnt lgkmcnt(3)
	v_mfma_f32_16x16x32_bf16 v[132:135], v[222:225], v[172:175], v[132:135]
	s_waitcnt lgkmcnt(1)
	v_mfma_f32_16x16x32_bf16 v[128:131], v[230:233], v[172:175], v[128:131]
	v_mfma_f32_16x16x32_bf16 v[116:119], v[222:225], v[198:201], v[116:119]
	v_mfma_f32_16x16x32_bf16 v[112:115], v[230:233], v[198:201], v[112:115]
	v_mfma_f32_16x16x32_bf16 v[100:103], v[222:225], v[206:209], v[100:103]
	v_mfma_f32_16x16x32_bf16 v[96:99], v[230:233], v[206:209], v[96:99]
	v_mfma_f32_16x16x32_bf16 v[84:87], v[222:225], v[214:217], v[84:87]
	v_mfma_f32_16x16x32_bf16 v[80:83], v[230:233], v[214:217], v[80:83]
	v_mfma_f32_16x16x32_bf16 v[132:135], v[226:229], v[176:179], v[132:135]
	s_waitcnt lgkmcnt(0)
	v_mfma_f32_16x16x32_bf16 v[128:131], v[234:237], v[176:179], v[128:131]
	v_mfma_f32_16x16x32_bf16 v[116:119], v[226:229], v[202:205], v[116:119]
	v_mfma_f32_16x16x32_bf16 v[112:115], v[234:237], v[202:205], v[112:115]
	v_mfma_f32_16x16x32_bf16 v[100:103], v[226:229], v[210:213], v[100:103]
	v_mfma_f32_16x16x32_bf16 v[96:99], v[234:237], v[210:213], v[96:99]
	v_mfma_f32_16x16x32_bf16 v[84:87], v[226:229], v[218:221], v[84:87]
	v_mfma_f32_16x16x32_bf16 v[80:83], v[234:237], v[218:221], v[80:83]
	s_setprio 0
	s_mov_b32 m0, s36
	v_lshl_add_u64 v[240:241], s[28:29], 0, v[162:163]
	s_barrier
	ds_read_b128 v[172:175], v196 offset:16384
	ds_read_b128 v[176:179], v196 offset:17408
	ds_read_b128 v[198:201], v196 offset:18432
	ds_read_b128 v[202:205], v196 offset:19456
	ds_read_b128 v[206:209], v196 offset:20480
	ds_read_b128 v[210:213], v196 offset:21504
	ds_read_b128 v[214:217], v196 offset:22528
	ds_read_b128 v[218:221], v196 offset:23552
	global_load_lds_dwordx4 v[240:241], off
	v_lshl_add_u64 v[242:243], s[28:29], 0, v[164:165]
	s_mov_b32 m0, s37
	s_nop 0
	global_load_lds_dwordx4 v[242:243], off
	s_barrier
	s_setprio 1
	s_waitcnt lgkmcnt(7)
	v_mfma_f32_16x16x32_bf16 v[76:79], v[24:27], v[172:175], v[76:79]
	v_mfma_f32_16x16x32_bf16 v[72:75], v[40:43], v[172:175], v[72:75]
	s_waitcnt lgkmcnt(5)
	v_mfma_f32_16x16x32_bf16 v[60:63], v[24:27], v[198:201], v[60:63]
	v_mfma_f32_16x16x32_bf16 v[56:59], v[40:43], v[198:201], v[56:59]
	s_waitcnt lgkmcnt(3)
	v_mfma_f32_16x16x32_bf16 v[36:39], v[24:27], v[206:209], v[36:39]
	v_mfma_f32_16x16x32_bf16 v[28:31], v[40:43], v[206:209], v[28:31]
	s_waitcnt lgkmcnt(1)
	v_mfma_f32_16x16x32_bf16 v[12:15], v[24:27], v[214:217], v[12:15]
	v_mfma_f32_16x16x32_bf16 v[8:11], v[40:43], v[214:217], v[8:11]
	v_mfma_f32_16x16x32_bf16 v[76:79], v[32:35], v[176:179], v[76:79]
	v_mfma_f32_16x16x32_bf16 v[72:75], v[44:47], v[176:179], v[72:75]
	v_mfma_f32_16x16x32_bf16 v[60:63], v[32:35], v[202:205], v[60:63]
	v_mfma_f32_16x16x32_bf16 v[56:59], v[44:47], v[202:205], v[56:59]
	v_mfma_f32_16x16x32_bf16 v[36:39], v[32:35], v[210:213], v[36:39]
	v_mfma_f32_16x16x32_bf16 v[28:31], v[44:47], v[210:213], v[28:31]
	s_waitcnt lgkmcnt(0)
	v_mfma_f32_16x16x32_bf16 v[12:15], v[32:35], v[218:221], v[12:15]
	v_mfma_f32_16x16x32_bf16 v[8:11], v[44:47], v[218:221], v[8:11]
	s_setprio 0
	s_barrier
	s_add_u32 s66, s26, 0x80000
	s_addc_u32 s67, s27, 0
	s_add_i32 s70, s70, s35
	v_lshl_add_u64 v[24:25], s[66:67], 0, v[144:145]
	s_mov_b32 m0, s70
	s_nop 0
	global_load_lds_dwordx4 v[24:25], off
	v_lshl_add_u64 v[24:25], s[66:67], 0, v[166:167]
	s_add_i32 m0, s70, 0x2000
	s_nop 0
	global_load_lds_dwordx4 v[24:25], off
	s_waitcnt vmcnt(6)
	s_barrier
	s_setprio 1
	v_mfma_f32_16x16x32_bf16 v[20:23], v[222:225], v[206:209], v[20:23]
	v_mfma_f32_16x16x32_bf16 v[16:19], v[230:233], v[206:209], v[16:19]
	v_mfma_f32_16x16x32_bf16 v[4:7], v[222:225], v[214:217], v[4:7]
	v_mfma_f32_16x16x32_bf16 v[0:3], v[230:233], v[214:217], v[0:3]
	v_mfma_f32_16x16x32_bf16 v[24:27], v[222:225], v[172:175], v[68:71]
	v_mfma_f32_16x16x32_bf16 v[32:35], v[230:233], v[172:175], v[64:67]
	v_mfma_f32_16x16x32_bf16 v[40:43], v[222:225], v[198:201], v[52:55]
	v_mfma_f32_16x16x32_bf16 v[44:47], v[230:233], v[198:201], v[48:51]
	v_mfma_f32_16x16x32_bf16 v[20:23], v[226:229], v[210:213], v[20:23]
	v_mfma_f32_16x16x32_bf16 v[16:19], v[234:237], v[210:213], v[16:19]
	v_mfma_f32_16x16x32_bf16 v[4:7], v[226:229], v[218:221], v[4:7]
	v_mfma_f32_16x16x32_bf16 v[0:3], v[234:237], v[218:221], v[0:3]
	v_mfma_f32_16x16x32_bf16 v[24:27], v[226:229], v[176:179], v[24:27]
	v_mfma_f32_16x16x32_bf16 v[32:35], v[234:237], v[176:179], v[32:35]
	v_mfma_f32_16x16x32_bf16 v[40:43], v[226:229], v[202:205], v[40:43]
	v_mfma_f32_16x16x32_bf16 v[44:47], v[234:237], v[202:205], v[44:47]
	s_setprio 0
	s_add_i32 s66, 0, 0x18000
	v_add_u32_e32 v68, s66, v194
	s_barrier
	ds_read_b128 v[48:51], v68
	ds_read_b128 v[52:55], v68 offset:1024
	ds_read_b128 v[64:67], v68 offset:2048
	ds_read_b128 v[68:71], v68 offset:3072
	s_add_u32 s28, s28, 0x80000
	s_addc_u32 s29, s29, 0
	s_mov_b32 m0, s50
	v_lshl_add_u64 v[222:223], s[28:29], 0, v[162:163]
	ds_read_b128 v[172:175], v196 offset:32768
	ds_read_b128 v[176:179], v196 offset:33792
	ds_read_b128 v[198:201], v196 offset:34816
	ds_read_b128 v[202:205], v196 offset:35840
	ds_read_b128 v[206:209], v196 offset:36864
	ds_read_b128 v[210:213], v196 offset:37888
	ds_read_b128 v[214:217], v196 offset:38912
	ds_read_b128 v[218:221], v196 offset:39936
	global_load_lds_dwordx4 v[222:223], off
	v_lshl_add_u64 v[222:223], s[28:29], 0, v[164:165]
	s_mov_b32 m0, s51
	s_nop 0
	global_load_lds_dwordx4 v[222:223], off
	s_waitcnt lgkmcnt(8)
	s_barrier
	s_setprio 1
	s_waitcnt lgkmcnt(7)
	v_mfma_f32_16x16x32_bf16 v[140:143], v[48:51], v[172:175], v[140:143]
	v_mfma_f32_16x16x32_bf16 v[136:139], v[64:67], v[172:175], v[136:139]
	s_waitcnt lgkmcnt(5)
	v_mfma_f32_16x16x32_bf16 v[124:127], v[48:51], v[198:201], v[124:127]
	v_mfma_f32_16x16x32_bf16 v[120:123], v[64:67], v[198:201], v[120:123]
	s_waitcnt lgkmcnt(3)
	v_mfma_f32_16x16x32_bf16 v[108:111], v[48:51], v[206:209], v[108:111]
	v_mfma_f32_16x16x32_bf16 v[104:107], v[64:67], v[206:209], v[104:107]
	s_waitcnt lgkmcnt(1)
	v_mfma_f32_16x16x32_bf16 v[92:95], v[48:51], v[214:217], v[92:95]
	v_mfma_f32_16x16x32_bf16 v[88:91], v[64:67], v[214:217], v[88:91]
	v_mfma_f32_16x16x32_bf16 v[140:143], v[52:55], v[176:179], v[140:143]
	v_mfma_f32_16x16x32_bf16 v[136:139], v[68:71], v[176:179], v[136:139]
	v_mfma_f32_16x16x32_bf16 v[124:127], v[52:55], v[202:205], v[124:127]
	v_mfma_f32_16x16x32_bf16 v[120:123], v[68:71], v[202:205], v[120:123]
	v_mfma_f32_16x16x32_bf16 v[108:111], v[52:55], v[210:213], v[108:111]
	v_mfma_f32_16x16x32_bf16 v[104:107], v[68:71], v[210:213], v[104:107]
	s_waitcnt lgkmcnt(0)
	v_mfma_f32_16x16x32_bf16 v[92:95], v[52:55], v[218:221], v[92:95]
	v_mfma_f32_16x16x32_bf16 v[88:91], v[68:71], v[218:221], v[88:91]
	s_setprio 0
	s_barrier
	s_add_i32 s28, 0, 0x1c000
	s_add_i32 s29, s66, s35
	v_add_u32_e32 v197, s28, v194
	v_lshl_add_u64 v[180:181], v[180:181], 0, s[86:87]
	s_mov_b32 m0, s29
	ds_read_b128 v[222:225], v197
	ds_read_b128 v[226:229], v197 offset:1024
	ds_read_b128 v[230:233], v197 offset:2048
	ds_read_b128 v[234:237], v197 offset:3072
	global_load_lds_dwordx4 v[180:181], off
	v_lshl_add_u64 v[180:181], v[238:239], 0, s[86:87]
	s_add_i32 m0, s29, 0x2000
	s_nop 0
	global_load_lds_dwordx4 v[180:181], off
	s_barrier
	s_setprio 1
	s_waitcnt lgkmcnt(3)
	v_mfma_f32_16x16x32_bf16 v[132:135], v[222:225], v[172:175], v[132:135]
	s_waitcnt lgkmcnt(1)
	v_mfma_f32_16x16x32_bf16 v[128:131], v[230:233], v[172:175], v[128:131]
	v_mfma_f32_16x16x32_bf16 v[116:119], v[222:225], v[198:201], v[116:119]
	v_mfma_f32_16x16x32_bf16 v[112:115], v[230:233], v[198:201], v[112:115]
	v_mfma_f32_16x16x32_bf16 v[100:103], v[222:225], v[206:209], v[100:103]
	v_mfma_f32_16x16x32_bf16 v[96:99], v[230:233], v[206:209], v[96:99]
	v_mfma_f32_16x16x32_bf16 v[84:87], v[222:225], v[214:217], v[84:87]
	v_mfma_f32_16x16x32_bf16 v[80:83], v[230:233], v[214:217], v[80:83]
	v_mfma_f32_16x16x32_bf16 v[132:135], v[226:229], v[176:179], v[132:135]
	s_waitcnt lgkmcnt(0)
	v_mfma_f32_16x16x32_bf16 v[128:131], v[234:237], v[176:179], v[128:131]
	v_mfma_f32_16x16x32_bf16 v[116:119], v[226:229], v[202:205], v[116:119]
	v_mfma_f32_16x16x32_bf16 v[112:115], v[234:237], v[202:205], v[112:115]
	v_mfma_f32_16x16x32_bf16 v[100:103], v[226:229], v[210:213], v[100:103]
	v_mfma_f32_16x16x32_bf16 v[96:99], v[234:237], v[210:213], v[96:99]
	v_mfma_f32_16x16x32_bf16 v[84:87], v[226:229], v[218:221], v[84:87]
	v_mfma_f32_16x16x32_bf16 v[80:83], v[234:237], v[218:221], v[80:83]
	s_setprio 0
	s_mov_b32 m0, s52
	v_lshl_add_u64 v[180:181], v[240:241], 0, s[86:87]
	s_barrier
	ds_read_b128 v[172:175], v196 offset:49152
	ds_read_b128 v[176:179], v196 offset:50176
	ds_read_b128 v[198:201], v196 offset:51200
	ds_read_b128 v[202:205], v196 offset:52224
	ds_read_b128 v[206:209], v196 offset:53248
	ds_read_b128 v[210:213], v196 offset:54272
	ds_read_b128 v[214:217], v196 offset:55296
	ds_read_b128 v[218:221], v196 offset:56320
	global_load_lds_dwordx4 v[180:181], off
	v_lshl_add_u64 v[180:181], v[242:243], 0, s[86:87]
	s_mov_b32 m0, s53
	s_nop 0
	global_load_lds_dwordx4 v[180:181], off
	s_barrier
	s_setprio 1
	s_waitcnt lgkmcnt(7)
	v_mfma_f32_16x16x32_bf16 v[76:79], v[48:51], v[172:175], v[76:79]
	v_mfma_f32_16x16x32_bf16 v[72:75], v[64:67], v[172:175], v[72:75]
	s_waitcnt lgkmcnt(5)
	v_mfma_f32_16x16x32_bf16 v[60:63], v[48:51], v[198:201], v[60:63]
	v_mfma_f32_16x16x32_bf16 v[56:59], v[64:67], v[198:201], v[56:59]
	s_waitcnt lgkmcnt(3)
	v_mfma_f32_16x16x32_bf16 v[36:39], v[48:51], v[206:209], v[36:39]
	v_mfma_f32_16x16x32_bf16 v[28:31], v[64:67], v[206:209], v[28:31]
	s_waitcnt lgkmcnt(1)
	v_mfma_f32_16x16x32_bf16 v[12:15], v[48:51], v[214:217], v[12:15]
	v_mfma_f32_16x16x32_bf16 v[8:11], v[64:67], v[214:217], v[8:11]
	v_mfma_f32_16x16x32_bf16 v[76:79], v[52:55], v[176:179], v[76:79]
	v_mfma_f32_16x16x32_bf16 v[72:75], v[68:71], v[176:179], v[72:75]
	v_mfma_f32_16x16x32_bf16 v[60:63], v[52:55], v[202:205], v[60:63]
	v_mfma_f32_16x16x32_bf16 v[56:59], v[68:71], v[202:205], v[56:59]
	v_mfma_f32_16x16x32_bf16 v[36:39], v[52:55], v[210:213], v[36:39]
	v_mfma_f32_16x16x32_bf16 v[28:31], v[68:71], v[210:213], v[28:31]
	s_waitcnt lgkmcnt(0)
	v_mfma_f32_16x16x32_bf16 v[12:15], v[52:55], v[218:221], v[12:15]
	v_mfma_f32_16x16x32_bf16 v[8:11], v[68:71], v[218:221], v[8:11]
	s_setprio 0
	s_barrier
	s_add_u32 s26, s26, 0x80080
	s_addc_u32 s27, s27, 0
	s_add_i32 s28, s28, s35
	v_lshl_add_u64 v[48:49], s[26:27], 0, v[144:145]
	s_mov_b32 m0, s28
	s_nop 0
	global_load_lds_dwordx4 v[48:49], off
	v_lshl_add_u64 v[48:49], s[26:27], 0, v[166:167]
	s_add_i32 m0, s28, 0x2000
	s_nop 0
	global_load_lds_dwordx4 v[48:49], off
	s_waitcnt vmcnt(6)
	s_barrier
	s_setprio 1
	v_mfma_f32_16x16x32_bf16 v[24:27], v[222:225], v[172:175], v[24:27]
	v_mfma_f32_16x16x32_bf16 v[68:71], v[226:229], v[176:179], v[24:27]
	v_mfma_f32_16x16x32_bf16 v[24:27], v[230:233], v[172:175], v[32:35]
	v_mfma_f32_16x16x32_bf16 v[64:67], v[234:237], v[176:179], v[24:27]
	v_mfma_f32_16x16x32_bf16 v[24:27], v[222:225], v[198:201], v[40:43]
	v_mfma_f32_16x16x32_bf16 v[52:55], v[226:229], v[202:205], v[24:27]
	v_mfma_f32_16x16x32_bf16 v[24:27], v[230:233], v[198:201], v[44:47]
	v_mfma_f32_16x16x32_bf16 v[20:23], v[222:225], v[206:209], v[20:23]
	v_mfma_f32_16x16x32_bf16 v[16:19], v[230:233], v[206:209], v[16:19]
	v_mfma_f32_16x16x32_bf16 v[4:7], v[222:225], v[214:217], v[4:7]
	v_mfma_f32_16x16x32_bf16 v[0:3], v[230:233], v[214:217], v[0:3]
	v_mfma_f32_16x16x32_bf16 v[48:51], v[234:237], v[202:205], v[24:27]
	v_mfma_f32_16x16x32_bf16 v[20:23], v[226:229], v[210:213], v[20:23]
	v_mfma_f32_16x16x32_bf16 v[16:19], v[234:237], v[210:213], v[16:19]
	v_mfma_f32_16x16x32_bf16 v[4:7], v[226:229], v[218:221], v[4:7]
	v_mfma_f32_16x16x32_bf16 v[0:3], v[234:237], v[218:221], v[0:3]
	s_setprio 0
	s_add_i32 s57, s57, 2
	s_add_u32 s6, s6, 0x100
	s_addc_u32 s7, s7, 0
	s_add_u32 s11, s11, 0x100
	s_addc_u32 s19, s19, 0
	s_cmp_gt_u32 s57, 29
	s_barrier
	s_cbranch_scc0 .LBB0_119
	s_load_dwordx2 s[6:7], s[20:21], 0x58
	v_lshl_or_b32 v172, s56, 8, v195
	v_ashrrev_i32_e32 v173, 31, v172
	s_cmp_gt_i32 s56, 7
	v_lshl_add_u32 v174, s10, 8, v193
	s_waitcnt lgkmcnt(0)
	v_lshl_add_u64 v[32:33], v[172:173], 2, s[6:7]
	global_load_dwordx4 v[40:43], v[32:33], off offset:16
	global_load_dwordx4 v[44:47], v[32:33], off
	global_load_dwordx4 v[24:27], v[32:33], off offset:528
	s_nop 0
	global_load_dwordx4 v[32:35], v[32:33], off offset:512
	s_cselect_b64 s[10:11], -1, 0
	s_lshl_b32 s6, s56, 2
	s_sub_i32 s6, s6, 32
	s_ashr_i32 s7, s6, 31
	s_or_b64 s[26:27], s[6:7], s[76:77]
	s_mov_b32 s6, 0x3e6d3388
	s_mov_b32 s28, 0xbf3a00e3
	v_ashrrev_i32_e32 v175, 31, v174
	v_lshlrev_b64 v[176:177], 13, v[174:175]
	v_lshl_add_u64 v[176:177], s[14:15], 0, v[176:177]
	v_lshl_add_u64 v[176:177], v[172:173], 1, v[176:177]
	s_cmp_lt_i32 s56, 8
	s_waitcnt vmcnt(0)
	v_pk_add_f32 v[136:137], v[136:137], v[40:41]
	v_pk_add_f32 v[140:141], v[140:141], v[44:45]
	v_pk_add_f32 v[142:143], v[142:143], v[46:47]
	v_and_b32_e32 v181, 0x7fffffff, v141
	v_and_b32_e32 v180, 0x7fffffff, v140
	v_pk_fma_f32 v[178:179], v[180:181], s[6:7], 1.0 op_sel_hi:[1,0,0]
	v_pk_mul_f32 v[202:203], v[140:141], v[140:141]
	v_rcp_f32_e32 v198, v178
	v_rcp_f32_e32 v199, v179
	v_mov_b64_e32 v[178:179], s[28:29]
	v_pk_mul_f32 v[202:203], v[202:203], s[60:61] op_sel_hi:[1,0]
	v_pk_add_f32 v[138:139], v[138:139], v[42:43]
	v_pk_fma_f32 v[200:201], v[198:199], s[92:93], v[178:179] op_sel_hi:[1,0,0]
	v_exp_f32_e32 v202, v202
	v_pk_fma_f32 v[200:201], v[198:199], v[200:201], s[96:97] op_sel_hi:[1,1,0]
	v_exp_f32_e32 v203, v203
	v_pk_fma_f32 v[200:201], v[198:199], v[200:201], s[44:45] op_sel_hi:[1,1,0]
	v_pk_add_f32 v[132:133], v[132:133], v[32:33]
	v_pk_fma_f32 v[200:201], v[198:199], v[200:201], s[58:59] op_sel_hi:[1,1,0]
	v_pk_add_f32 v[134:135], v[134:135], v[34:35]
	v_pk_mul_f32 v[198:199], v[198:199], v[200:201]
	v_pk_mul_f32 v[200:201], v[142:143], v[142:143]
	v_pk_fma_f32 v[198:199], v[202:203], v[198:199], 0.5 op_sel_hi:[1,1,0] neg_lo:[1,0,0] neg_hi:[1,0,0]
	v_pk_mul_f32 v[200:201], v[200:201], s[60:61] op_sel_hi:[1,0]
	v_pk_mul_f32 v[180:181], v[180:181], v[198:199]
	v_exp_f32_e32 v200, v200
	v_pk_fma_f32 v[140:141], v[140:141], 0.5, v[180:181] op_sel_hi:[1,0,1]
	v_and_b32_e32 v181, 0x7fffffff, v143
	v_and_b32_e32 v180, 0x7fffffff, v142
	v_pk_fma_f32 v[198:199], v[180:181], s[6:7], 1.0 op_sel_hi:[1,0,0]
	v_exp_f32_e32 v201, v201
	v_rcp_f32_e32 v198, v198
	v_rcp_f32_e32 v199, v199
	v_pk_add_f32 v[128:129], v[128:129], v[24:25]
	v_pk_add_f32 v[130:131], v[130:131], v[26:27]
	v_pk_fma_f32 v[202:203], v[198:199], s[92:93], v[178:179] op_sel_hi:[1,0,0]
	s_nop 0
	v_pk_fma_f32 v[202:203], v[198:199], v[202:203], s[96:97] op_sel_hi:[1,1,0]
	s_nop 0
	v_pk_fma_f32 v[202:203], v[198:199], v[202:203], s[44:45] op_sel_hi:[1,1,0]
	s_nop 0
	v_pk_fma_f32 v[202:203], v[198:199], v[202:203], s[58:59] op_sel_hi:[1,1,0]
	s_nop 0
	v_pk_mul_f32 v[198:199], v[198:199], v[202:203]
	v_pk_mul_f32 v[202:203], v[136:137], v[136:137]
	v_pk_fma_f32 v[198:199], v[200:201], v[198:199], 0.5 op_sel_hi:[1,1,0] neg_lo:[1,0,0] neg_hi:[1,0,0]
	v_pk_mul_f32 v[202:203], v[202:203], s[60:61] op_sel_hi:[1,0]
	v_pk_mul_f32 v[180:181], v[180:181], v[198:199]
	v_exp_f32_e32 v202, v202
	v_pk_fma_f32 v[142:143], v[142:143], 0.5, v[180:181] op_sel_hi:[1,0,1]
	v_and_b32_e32 v181, 0x7fffffff, v137
	v_and_b32_e32 v180, 0x7fffffff, v136
	v_pk_fma_f32 v[198:199], v[180:181], s[6:7], 1.0 op_sel_hi:[1,0,0]
	v_exp_f32_e32 v203, v203
	v_rcp_f32_e32 v198, v198
	v_rcp_f32_e32 v199, v199
	s_nop 0
	v_pk_fma_f32 v[200:201], v[198:199], s[92:93], v[178:179] op_sel_hi:[1,0,0]
	s_nop 0
	v_pk_fma_f32 v[200:201], v[198:199], v[200:201], s[96:97] op_sel_hi:[1,1,0]
	s_nop 0
	v_pk_fma_f32 v[200:201], v[198:199], v[200:201], s[44:45] op_sel_hi:[1,1,0]
	s_nop 0
	v_pk_fma_f32 v[200:201], v[198:199], v[200:201], s[58:59] op_sel_hi:[1,1,0]
	s_nop 0
	v_pk_mul_f32 v[198:199], v[198:199], v[200:201]
	v_pk_mul_f32 v[200:201], v[138:139], v[138:139]
	v_pk_fma_f32 v[198:199], v[202:203], v[198:199], 0.5 op_sel_hi:[1,1,0] neg_lo:[1,0,0] neg_hi:[1,0,0]
	v_pk_mul_f32 v[200:201], v[200:201], s[60:61] op_sel_hi:[1,0]
	v_pk_mul_f32 v[180:181], v[180:181], v[198:199]
	v_exp_f32_e32 v200, v200
	v_pk_fma_f32 v[136:137], v[136:137], 0.5, v[180:181] op_sel_hi:[1,0,1]
	v_and_b32_e32 v181, 0x7fffffff, v139
	v_and_b32_e32 v180, 0x7fffffff, v138
	v_pk_fma_f32 v[198:199], v[180:181], s[6:7], 1.0 op_sel_hi:[1,0,0]
	v_exp_f32_e32 v201, v201
	v_rcp_f32_e32 v198, v198
	v_rcp_f32_e32 v199, v199
	s_nop 0
	v_pk_fma_f32 v[202:203], v[198:199], s[92:93], v[178:179] op_sel_hi:[1,0,0]
	s_nop 0
	v_pk_fma_f32 v[202:203], v[198:199], v[202:203], s[96:97] op_sel_hi:[1,1,0]
	s_nop 0
	v_pk_fma_f32 v[202:203], v[198:199], v[202:203], s[44:45] op_sel_hi:[1,1,0]
	s_nop 0
	v_pk_fma_f32 v[202:203], v[198:199], v[202:203], s[58:59] op_sel_hi:[1,1,0]
	s_nop 0
	v_pk_mul_f32 v[198:199], v[198:199], v[202:203]
	v_pk_mul_f32 v[202:203], v[132:133], v[132:133]
	v_pk_fma_f32 v[198:199], v[200:201], v[198:199], 0.5 op_sel_hi:[1,1,0] neg_lo:[1,0,0] neg_hi:[1,0,0]
	v_cvt_pk_bf16_f32 v200, v136, v137
	v_pk_mul_f32 v[202:203], v[202:203], s[60:61] op_sel_hi:[1,0]
	v_pk_mul_f32 v[180:181], v[180:181], v[198:199]
	v_cvt_pk_bf16_f32 v198, v140, v141
	v_cvt_pk_bf16_f32 v199, v142, v143
	v_exp_f32_e32 v202, v202
	v_pk_fma_f32 v[138:139], v[138:139], 0.5, v[180:181] op_sel_hi:[1,0,1]
	v_and_b32_e32 v181, 0x7fffffff, v133
	v_and_b32_e32 v180, 0x7fffffff, v132
	v_cvt_pk_bf16_f32 v201, v138, v139
	global_store_dwordx4 v[176:177], v[198:201], off
	v_exp_f32_e32 v203, v203
	s_nop 0
	v_pk_fma_f32 v[198:199], v[180:181], s[6:7], 1.0 op_sel_hi:[1,0,0]
	s_nop 0
	v_rcp_f32_e32 v198, v198
	v_rcp_f32_e32 v199, v199
	s_nop 0
	v_pk_fma_f32 v[200:201], v[198:199], s[92:93], v[178:179] op_sel_hi:[1,0,0]
	s_nop 0
	v_pk_fma_f32 v[200:201], v[198:199], v[200:201], s[96:97] op_sel_hi:[1,1,0]
	s_nop 0
	v_pk_fma_f32 v[200:201], v[198:199], v[200:201], s[44:45] op_sel_hi:[1,1,0]
	s_nop 0
	v_pk_fma_f32 v[200:201], v[198:199], v[200:201], s[58:59] op_sel_hi:[1,1,0]
	s_nop 0
	v_pk_mul_f32 v[198:199], v[198:199], v[200:201]
	v_pk_mul_f32 v[200:201], v[134:135], v[134:135]
	v_pk_fma_f32 v[198:199], v[202:203], v[198:199], 0.5 op_sel_hi:[1,1,0] neg_lo:[1,0,0] neg_hi:[1,0,0]
	v_pk_mul_f32 v[200:201], v[200:201], s[60:61] op_sel_hi:[1,0]
	v_pk_mul_f32 v[180:181], v[180:181], v[198:199]
	v_exp_f32_e32 v200, v200
	v_pk_fma_f32 v[132:133], v[132:133], 0.5, v[180:181] op_sel_hi:[1,0,1]
	v_and_b32_e32 v181, 0x7fffffff, v135
	v_and_b32_e32 v180, 0x7fffffff, v134
	v_pk_fma_f32 v[198:199], v[180:181], s[6:7], 1.0 op_sel_hi:[1,0,0]
	v_exp_f32_e32 v201, v201
	v_rcp_f32_e32 v198, v198
	v_rcp_f32_e32 v199, v199
	s_nop 0
	v_pk_fma_f32 v[202:203], v[198:199], s[92:93], v[178:179] op_sel_hi:[1,0,0]
	s_nop 0
	v_pk_fma_f32 v[202:203], v[198:199], v[202:203], s[96:97] op_sel_hi:[1,1,0]
	s_nop 0
	v_pk_fma_f32 v[202:203], v[198:199], v[202:203], s[44:45] op_sel_hi:[1,1,0]
	s_nop 0
	v_pk_fma_f32 v[202:203], v[198:199], v[202:203], s[58:59] op_sel_hi:[1,1,0]
	s_nop 0
	v_pk_mul_f32 v[198:199], v[198:199], v[202:203]
	v_pk_mul_f32 v[202:203], v[128:129], v[128:129]
	v_pk_fma_f32 v[198:199], v[200:201], v[198:199], 0.5 op_sel_hi:[1,1,0] neg_lo:[1,0,0] neg_hi:[1,0,0]
	v_pk_mul_f32 v[202:203], v[202:203], s[60:61] op_sel_hi:[1,0]
	v_pk_mul_f32 v[180:181], v[180:181], v[198:199]
	v_exp_f32_e32 v202, v202
	v_pk_fma_f32 v[134:135], v[134:135], 0.5, v[180:181] op_sel_hi:[1,0,1]
	v_and_b32_e32 v181, 0x7fffffff, v129
	v_and_b32_e32 v180, 0x7fffffff, v128
	v_pk_fma_f32 v[198:199], v[180:181], s[6:7], 1.0 op_sel_hi:[1,0,0]
	v_exp_f32_e32 v203, v203
	v_rcp_f32_e32 v198, v198
	v_rcp_f32_e32 v199, v199
	s_nop 0
	v_pk_fma_f32 v[200:201], v[198:199], s[92:93], v[178:179] op_sel_hi:[1,0,0]
	s_nop 0
	v_pk_fma_f32 v[200:201], v[198:199], v[200:201], s[96:97] op_sel_hi:[1,1,0]
	s_nop 0
	v_pk_fma_f32 v[200:201], v[198:199], v[200:201], s[44:45] op_sel_hi:[1,1,0]
	s_nop 0
	v_pk_fma_f32 v[200:201], v[198:199], v[200:201], s[58:59] op_sel_hi:[1,1,0]
	s_nop 0
	v_pk_mul_f32 v[198:199], v[198:199], v[200:201]
	v_pk_mul_f32 v[200:201], v[130:131], v[130:131]
	v_pk_fma_f32 v[198:199], v[202:203], v[198:199], 0.5 op_sel_hi:[1,1,0] neg_lo:[1,0,0] neg_hi:[1,0,0]
	s_nop 0
	v_pk_mul_f32 v[180:181], v[180:181], v[198:199]
	s_nop 0
	v_pk_fma_f32 v[128:129], v[128:129], 0.5, v[180:181] op_sel_hi:[1,0,1]
	v_and_b32_e32 v181, 0x7fffffff, v131
	v_and_b32_e32 v180, 0x7fffffff, v130
	v_pk_fma_f32 v[198:199], v[180:181], s[6:7], 1.0 op_sel_hi:[1,0,0]
	s_nop 0
	v_rcp_f32_e32 v198, v198
	v_rcp_f32_e32 v199, v199
	s_nop 0
	v_pk_fma_f32 v[178:179], v[198:199], s[92:93], v[178:179] op_sel_hi:[1,0,0]
	s_nop 0
	v_pk_fma_f32 v[178:179], v[198:199], v[178:179], s[96:97] op_sel_hi:[1,1,0]
	s_nop 0
	v_pk_fma_f32 v[178:179], v[198:199], v[178:179], s[44:45] op_sel_hi:[1,1,0]
	s_nop 0
	v_pk_fma_f32 v[178:179], v[198:199], v[178:179], s[58:59] op_sel_hi:[1,1,0]
	s_nop 0
	v_pk_mul_f32 v[178:179], v[198:199], v[178:179]
	v_pk_mul_f32 v[198:199], v[200:201], s[60:61] op_sel_hi:[1,0]
	s_nop 0
	v_exp_f32_e32 v198, v198
	v_exp_f32_e32 v199, v199
	s_nop 0
	v_pk_fma_f32 v[178:179], v[198:199], v[178:179], 0.5 op_sel_hi:[1,1,0] neg_lo:[1,0,0] neg_hi:[1,0,0]
	s_nop 0
	v_pk_mul_f32 v[178:179], v[180:181], v[178:179]
	v_cvt_pk_bf16_f32 v180, v128, v129
	s_nop 0
	v_pk_fma_f32 v[130:131], v[130:131], 0.5, v[178:179] op_sel_hi:[1,0,1]
	v_cvt_pk_bf16_f32 v178, v132, v133
	v_cvt_pk_bf16_f32 v179, v134, v135
	s_nop 0
	v_cvt_pk_bf16_f32 v181, v130, v131
	global_store_dwordx4 v[176:177], v[178:181], off offset:256
	s_cbranch_scc1 .LBB0_124
	v_pk_mul_f32 v[202:203], v[134:135], v[134:135]
	v_mov_b32_e32 v206, v132
	v_mov_b32_e32 v207, v134
	v_mov_b32_e32 v134, v133
	v_mov_b32_e32 v180, v141
	v_mov_b32_e32 v181, v143
	v_pk_mul_f32 v[200:201], v[132:133], v[132:133]
	v_pk_add_f32 v[132:133], v[206:207], v[134:135]
	v_mov_b32_e32 v178, v140
	v_mov_b32_e32 v179, v142
	v_pk_mul_f32 v[180:181], v[180:181], v[180:181]
	v_pk_add_f32 v[132:133], v[132:133], v[132:133] op_sel:[0,1] op_sel_hi:[1,0]
	v_pk_fma_f32 v[178:179], v[178:179], v[178:179], v[180:181]
	v_pk_mul_f32 v[204:205], v[128:129], v[128:129]
	v_pk_add_f32 v[140:141], v[140:141], v[140:141] op_sel:[0,1] op_sel_hi:[1,0]
	v_pk_add_f32 v[142:143], v[142:143], v[142:143] op_sel:[0,1] op_sel_hi:[1,0]
	v_pk_add_f32 v[128:129], v[128:129], v[128:129] op_sel:[0,1] op_sel_hi:[1,0]
	v_and_b32_e32 v133, 64, v189
	v_pk_add_f32 v[178:179], v[178:179], v[178:179] op_sel_hi:[0,1]
	v_xor_b32_e32 v129, 16, v189
	v_add_u32_e32 v197, 64, v133
	v_mov_b32_e32 v141, v200
	v_mov_b32_e32 v143, v201
	v_pk_mul_f32 v[176:177], v[138:139], v[138:139]
	v_mul_f32_e32 v178, v136, v136
	v_cmp_lt_i32_e32 vcc, v129, v197
	v_mov_b32_e32 v134, v138
	v_mov_b32_e32 v135, v204
	v_mov_b32_e32 v204, v139
	v_pk_add_f32 v[138:139], v[140:141], v[142:143]
	v_mov_b32_e32 v140, v136
	v_mov_b32_e32 v141, v202
	v_mov_b32_e32 v202, v137
	v_pk_fma_f32 v[180:181], v[136:137], v[136:137], v[178:179] op_sel_hi:[1,1,0]
	v_mul_f32_e32 v178, v130, v130
	v_cndmask_b32_e32 v129, v189, v129, vcc
	v_pk_add_f32 v[136:137], v[140:141], v[202:203]
	v_pk_fma_f32 v[198:199], v[130:131], v[130:131], v[178:179] op_sel_hi:[1,1,0]
	v_lshlrev_b32_e32 v206, 2, v129
	v_pk_add_f32 v[134:135], v[134:135], v[204:205]
	v_pk_add_f32 v[136:137], v[138:139], v[136:137]
	v_mov_b32_e32 v178, v130
	v_mov_b32_e32 v180, v131
	v_mov_b32_e32 v133, v176
	v_mov_b32_e32 v129, v177
	v_pk_add_f32 v[134:135], v[136:137], v[134:135]
	v_mov_b32_e32 v198, v145
	v_pk_add_f32 v[130:131], v[178:179], v[180:181]
	v_pk_add_f32 v[128:129], v[132:133], v[128:129]
	v_pk_add_f32 v[134:135], v[134:135], v[198:199]
	v_pk_add_f32 v[128:129], v[128:129], v[130:131]
	v_xor_b32_e32 v132, 32, v189
	v_pk_add_f32 v[128:129], v[128:129], v[134:135]
	ds_bpermute_b32 v130, v206, v128
	ds_bpermute_b32 v131, v206, v129
	v_cmp_lt_i32_e32 vcc, v132, v197
	s_waitcnt lgkmcnt(0)
	v_pk_add_f32 v[128:129], v[128:129], v[130:131]
	v_cndmask_b32_e32 v132, v189, v132, vcc
	v_lshlrev_b32_e32 v132, 2, v132
	ds_bpermute_b32 v130, v132, v128
	ds_bpermute_b32 v131, v132, v129
	s_and_saveexec_b64 s[6:7], s[0:1]
	s_cbranch_execz .LBB0_123
	v_lshlrev_b64 v[132:133], 8, v[174:175]
	s_waitcnt lgkmcnt(0)
	v_pk_add_f32 v[128:129], v[128:129], v[130:131]
	v_lshl_add_u64 v[130:131], s[16:17], 0, v[132:133]
	v_lshl_add_u64 v[130:131], s[26:27], 3, v[130:131]
	global_store_dwordx2 v[130:131], v[128:129], off

.LBB0_700:
	s_add_u32 s28, s26, 0xfff80080
	s_addc_u32 s29, s27, -1
	s_add_i32 s71, 0, 0x10000
	v_add_u32_e32 v172, s71, v143
	ds_read_b128 v[138:141], v172
	ds_read_b128 v[164:167], v172 offset:1024
	ds_read_b128 v[168:171], v172 offset:2048
	ds_read_b128 v[172:175], v172 offset:3072
	s_cmp_eq_u32 s70, 28
	s_cselect_b32 s31, s7, s29
	s_cselect_b32 s30, s6, s28
	s_cselect_b32 s29, s9, s67
	s_cselect_b32 s28, s8, s21
	v_lshl_add_u64 v[180:181], s[26:27], 0, v[134:135]
	s_add_i32 m0, s51, 0xc000
	ds_read_b128 v[176:179], v163
	ds_read_b128 v[194:197], v163 offset:1024
	ds_read_b128 v[198:201], v163 offset:2048
	ds_read_b128 v[202:205], v163 offset:3072
	ds_read_b128 v[206:209], v163 offset:4096
	ds_read_b128 v[210:213], v163 offset:5120
	ds_read_b128 v[214:217], v163 offset:6144
	ds_read_b128 v[218:221], v163 offset:7168
	global_load_lds_dwordx4 v[180:181], off
	v_lshl_add_u64 v[180:181], s[26:27], 0, v[136:137]
	s_add_i32 m0, s51, 0xe000
	s_nop 0
	global_load_lds_dwordx4 v[180:181], off
	s_waitcnt lgkmcnt(8)
	s_barrier
	s_setprio 1
	s_waitcnt lgkmcnt(7)
	v_mfma_f32_16x16x32_bf16 v[124:127], v[138:141], v[176:179], v[124:127]
	v_mfma_f32_16x16x32_bf16 v[116:119], v[168:171], v[176:179], v[116:119]
	s_waitcnt lgkmcnt(5)
	v_mfma_f32_16x16x32_bf16 v[108:111], v[138:141], v[198:201], v[108:111]
	v_mfma_f32_16x16x32_bf16 v[100:103], v[168:171], v[198:201], v[100:103]
	s_waitcnt lgkmcnt(3)
	v_mfma_f32_16x16x32_bf16 v[92:95], v[138:141], v[206:209], v[92:95]
	v_mfma_f32_16x16x32_bf16 v[84:87], v[168:171], v[206:209], v[84:87]
	s_waitcnt lgkmcnt(1)
	v_mfma_f32_16x16x32_bf16 v[76:79], v[138:141], v[214:217], v[76:79]
	v_mfma_f32_16x16x32_bf16 v[68:71], v[168:171], v[214:217], v[68:71]
	v_mfma_f32_16x16x32_bf16 v[124:127], v[164:167], v[194:197], v[124:127]
	v_mfma_f32_16x16x32_bf16 v[116:119], v[172:175], v[194:197], v[116:119]
	v_mfma_f32_16x16x32_bf16 v[108:111], v[164:167], v[202:205], v[108:111]
	v_mfma_f32_16x16x32_bf16 v[100:103], v[172:175], v[202:205], v[100:103]
	v_mfma_f32_16x16x32_bf16 v[92:95], v[164:167], v[210:213], v[92:95]
	v_mfma_f32_16x16x32_bf16 v[84:87], v[172:175], v[210:213], v[84:87]
	s_waitcnt lgkmcnt(0)
	v_mfma_f32_16x16x32_bf16 v[76:79], v[164:167], v[218:221], v[76:79]
	v_mfma_f32_16x16x32_bf16 v[68:71], v[172:175], v[218:221], v[68:71]
	s_setprio 0
	s_barrier
	s_add_i32 s74, 0, 0x14000
	v_add_u32_e32 v180, s74, v143
	s_add_i32 s71, s71, s50
	ds_read_b128 v[222:225], v180
	ds_read_b128 v[226:229], v180 offset:1024
	ds_read_b128 v[230:233], v180 offset:2048
	ds_read_b128 v[234:237], v180 offset:3072
	v_lshl_add_u64 v[180:181], s[28:29], 0, v[144:145]
	s_mov_b32 m0, s71
	v_lshl_add_u64 v[238:239], s[28:29], 0, v[128:129]
	global_load_lds_dwordx4 v[180:181], off
	s_add_i32 m0, s71, 0x2000
	s_nop 0
	global_load_lds_dwordx4 v[238:239], off
	s_barrier
	s_setprio 1
	s_waitcnt lgkmcnt(3)
	v_mfma_f32_16x16x32_bf16 v[120:123], v[222:225], v[176:179], v[120:123]
	s_waitcnt lgkmcnt(1)
	v_mfma_f32_16x16x32_bf16 v[112:115], v[230:233], v[176:179], v[112:115]
	v_mfma_f32_16x16x32_bf16 v[104:107], v[222:225], v[198:201], v[104:107]
	v_mfma_f32_16x16x32_bf16 v[96:99], v[230:233], v[198:201], v[96:99]
	v_mfma_f32_16x16x32_bf16 v[88:91], v[222:225], v[206:209], v[88:91]
	v_mfma_f32_16x16x32_bf16 v[80:83], v[230:233], v[206:209], v[80:83]
	v_mfma_f32_16x16x32_bf16 v[72:75], v[222:225], v[214:217], v[72:75]
	v_mfma_f32_16x16x32_bf16 v[64:67], v[230:233], v[214:217], v[64:67]
	v_mfma_f32_16x16x32_bf16 v[120:123], v[226:229], v[194:197], v[120:123]
	s_waitcnt lgkmcnt(0)
	v_mfma_f32_16x16x32_bf16 v[112:115], v[234:237], v[194:197], v[112:115]
	v_mfma_f32_16x16x32_bf16 v[104:107], v[226:229], v[202:205], v[104:107]
	v_mfma_f32_16x16x32_bf16 v[96:99], v[234:237], v[202:205], v[96:99]
	v_mfma_f32_16x16x32_bf16 v[88:91], v[226:229], v[210:213], v[88:91]
	v_mfma_f32_16x16x32_bf16 v[80:83], v[234:237], v[210:213], v[80:83]
	v_mfma_f32_16x16x32_bf16 v[72:75], v[226:229], v[218:221], v[72:75]
	v_mfma_f32_16x16x32_bf16 v[64:67], v[234:237], v[218:221], v[64:67]
	s_setprio 0
	s_mov_b32 m0, s51
	v_lshl_add_u64 v[240:241], s[30:31], 0, v[132:133]
	s_barrier
	ds_read_b128 v[176:179], v163 offset:16384
	ds_read_b128 v[194:197], v163 offset:17408
	ds_read_b128 v[198:201], v163 offset:18432
	ds_read_b128 v[202:205], v163 offset:19456
	ds_read_b128 v[206:209], v163 offset:20480
	ds_read_b128 v[210:213], v163 offset:21504
	ds_read_b128 v[214:217], v163 offset:22528
	ds_read_b128 v[218:221], v163 offset:23552
	global_load_lds_dwordx4 v[240:241], off
	v_lshl_add_u64 v[242:243], s[30:31], 0, v[130:131]
	s_mov_b32 m0, s52
	s_nop 0
	global_load_lds_dwordx4 v[242:243], off
	s_barrier
	s_setprio 1
	s_waitcnt lgkmcnt(7)
	v_mfma_f32_16x16x32_bf16 v[60:63], v[138:141], v[176:179], v[60:63]
	v_mfma_f32_16x16x32_bf16 v[52:55], v[168:171], v[176:179], v[52:55]
	s_waitcnt lgkmcnt(5)
	v_mfma_f32_16x16x32_bf16 v[44:47], v[138:141], v[198:201], v[44:47]
	v_mfma_f32_16x16x32_bf16 v[36:39], v[168:171], v[198:201], v[36:39]
	s_waitcnt lgkmcnt(3)
	v_mfma_f32_16x16x32_bf16 v[28:31], v[138:141], v[206:209], v[28:31]
	v_mfma_f32_16x16x32_bf16 v[20:23], v[168:171], v[206:209], v[20:23]
	s_waitcnt lgkmcnt(1)
	v_mfma_f32_16x16x32_bf16 v[12:15], v[138:141], v[214:217], v[12:15]
	v_mfma_f32_16x16x32_bf16 v[4:7], v[168:171], v[214:217], v[4:7]
	v_mfma_f32_16x16x32_bf16 v[60:63], v[164:167], v[194:197], v[60:63]
	v_mfma_f32_16x16x32_bf16 v[52:55], v[172:175], v[194:197], v[52:55]
	v_mfma_f32_16x16x32_bf16 v[44:47], v[164:167], v[202:205], v[44:47]
	v_mfma_f32_16x16x32_bf16 v[36:39], v[172:175], v[202:205], v[36:39]
	v_mfma_f32_16x16x32_bf16 v[28:31], v[164:167], v[210:213], v[28:31]
	v_mfma_f32_16x16x32_bf16 v[20:23], v[172:175], v[210:213], v[20:23]
	s_waitcnt lgkmcnt(0)
	v_mfma_f32_16x16x32_bf16 v[12:15], v[164:167], v[218:221], v[12:15]
	v_mfma_f32_16x16x32_bf16 v[4:7], v[172:175], v[218:221], v[4:7]
	s_setprio 0
	s_barrier
	s_add_u32 s72, s28, 0x80000
	s_addc_u32 s73, s29, 0
	s_add_i32 s71, s74, s50
	v_lshl_add_u64 v[138:139], s[72:73], 0, v[144:145]
	s_mov_b32 m0, s71
	s_nop 0
	global_load_lds_dwordx4 v[138:139], off
	v_lshl_add_u64 v[138:139], s[72:73], 0, v[128:129]
	s_add_i32 m0, s71, 0x2000
	s_nop 0
	global_load_lds_dwordx4 v[138:139], off
	s_waitcnt vmcnt(6)
	s_barrier
	s_setprio 1
	v_mfma_f32_16x16x32_bf16 v[56:59], v[222:225], v[176:179], v[56:59]
	v_mfma_f32_16x16x32_bf16 v[48:51], v[230:233], v[176:179], v[48:51]
	v_mfma_f32_16x16x32_bf16 v[40:43], v[222:225], v[198:201], v[40:43]
	v_mfma_f32_16x16x32_bf16 v[32:35], v[230:233], v[198:201], v[32:35]
	v_mfma_f32_16x16x32_bf16 v[24:27], v[222:225], v[206:209], v[24:27]
	v_mfma_f32_16x16x32_bf16 v[16:19], v[230:233], v[206:209], v[16:19]
	v_mfma_f32_16x16x32_bf16 v[8:11], v[222:225], v[214:217], v[8:11]
	v_mfma_f32_16x16x32_bf16 v[0:3], v[230:233], v[214:217], v[0:3]
	v_mfma_f32_16x16x32_bf16 v[56:59], v[226:229], v[194:197], v[56:59]
	v_mfma_f32_16x16x32_bf16 v[48:51], v[234:237], v[194:197], v[48:51]
	v_mfma_f32_16x16x32_bf16 v[40:43], v[226:229], v[202:205], v[40:43]
	v_mfma_f32_16x16x32_bf16 v[32:35], v[234:237], v[202:205], v[32:35]
	v_mfma_f32_16x16x32_bf16 v[24:27], v[226:229], v[210:213], v[24:27]
	v_mfma_f32_16x16x32_bf16 v[16:19], v[234:237], v[210:213], v[16:19]
	v_mfma_f32_16x16x32_bf16 v[8:11], v[226:229], v[218:221], v[8:11]
	v_mfma_f32_16x16x32_bf16 v[0:3], v[234:237], v[218:221], v[0:3]
	s_setprio 0
	s_add_i32 s71, 0, 0x18000
	v_add_u32_e32 v172, s71, v143
	s_barrier
	ds_read_b128 v[138:141], v172
	ds_read_b128 v[164:167], v172 offset:1024
	ds_read_b128 v[168:171], v172 offset:2048
	ds_read_b128 v[172:175], v172 offset:3072
	s_add_u32 s30, s30, 0x80000
	s_addc_u32 s31, s31, 0
	s_mov_b32 m0, s53
	v_lshl_add_u64 v[222:223], s[30:31], 0, v[132:133]
	ds_read_b128 v[176:179], v163 offset:32768
	ds_read_b128 v[194:197], v163 offset:33792
	ds_read_b128 v[198:201], v163 offset:34816
	ds_read_b128 v[202:205], v163 offset:35840
	ds_read_b128 v[206:209], v163 offset:36864
	ds_read_b128 v[210:213], v163 offset:37888
	ds_read_b128 v[214:217], v163 offset:38912
	ds_read_b128 v[218:221], v163 offset:39936
	global_load_lds_dwordx4 v[222:223], off
	v_lshl_add_u64 v[222:223], s[30:31], 0, v[130:131]
	s_mov_b32 m0, s54
	s_nop 0
	global_load_lds_dwordx4 v[222:223], off
	s_waitcnt lgkmcnt(8)
	s_barrier
	s_setprio 1
	s_waitcnt lgkmcnt(7)
	v_mfma_f32_16x16x32_bf16 v[124:127], v[138:141], v[176:179], v[124:127]
	v_mfma_f32_16x16x32_bf16 v[116:119], v[168:171], v[176:179], v[116:119]
	s_waitcnt lgkmcnt(5)
	v_mfma_f32_16x16x32_bf16 v[108:111], v[138:141], v[198:201], v[108:111]
	v_mfma_f32_16x16x32_bf16 v[100:103], v[168:171], v[198:201], v[100:103]
	s_waitcnt lgkmcnt(3)
	v_mfma_f32_16x16x32_bf16 v[92:95], v[138:141], v[206:209], v[92:95]
	v_mfma_f32_16x16x32_bf16 v[84:87], v[168:171], v[206:209], v[84:87]
	s_waitcnt lgkmcnt(1)
	v_mfma_f32_16x16x32_bf16 v[76:79], v[138:141], v[214:217], v[76:79]
	v_mfma_f32_16x16x32_bf16 v[68:71], v[168:171], v[214:217], v[68:71]
	v_mfma_f32_16x16x32_bf16 v[124:127], v[164:167], v[194:197], v[124:127]
	v_mfma_f32_16x16x32_bf16 v[116:119], v[172:175], v[194:197], v[116:119]
	v_mfma_f32_16x16x32_bf16 v[108:111], v[164:167], v[202:205], v[108:111]
	v_mfma_f32_16x16x32_bf16 v[100:103], v[172:175], v[202:205], v[100:103]
	v_mfma_f32_16x16x32_bf16 v[92:95], v[164:167], v[210:213], v[92:95]
	v_mfma_f32_16x16x32_bf16 v[84:87], v[172:175], v[210:213], v[84:87]
	s_waitcnt lgkmcnt(0)
	v_mfma_f32_16x16x32_bf16 v[76:79], v[164:167], v[218:221], v[76:79]
	v_mfma_f32_16x16x32_bf16 v[68:71], v[172:175], v[218:221], v[68:71]
	s_setprio 0
	s_barrier
	s_add_i32 s30, 0, 0x1c000
	s_add_i32 s31, s71, s50
	v_add_u32_e32 v193, s30, v143
	v_lshl_add_u64 v[180:181], v[180:181], 0, s[86:87]
	s_mov_b32 m0, s31
	ds_read_b128 v[222:225], v193
	ds_read_b128 v[226:229], v193 offset:1024
	ds_read_b128 v[230:233], v193 offset:2048
	ds_read_b128 v[234:237], v193 offset:3072
	global_load_lds_dwordx4 v[180:181], off
	v_lshl_add_u64 v[180:181], v[238:239], 0, s[86:87]
	s_add_i32 m0, s31, 0x2000
	s_nop 0
	global_load_lds_dwordx4 v[180:181], off
	s_barrier
	s_setprio 1
	s_waitcnt lgkmcnt(3)
	v_mfma_f32_16x16x32_bf16 v[120:123], v[222:225], v[176:179], v[120:123]
	s_waitcnt lgkmcnt(1)
	v_mfma_f32_16x16x32_bf16 v[112:115], v[230:233], v[176:179], v[112:115]
	v_mfma_f32_16x16x32_bf16 v[104:107], v[222:225], v[198:201], v[104:107]
	v_mfma_f32_16x16x32_bf16 v[96:99], v[230:233], v[198:201], v[96:99]
	v_mfma_f32_16x16x32_bf16 v[88:91], v[222:225], v[206:209], v[88:91]
	v_mfma_f32_16x16x32_bf16 v[80:83], v[230:233], v[206:209], v[80:83]
	v_mfma_f32_16x16x32_bf16 v[72:75], v[222:225], v[214:217], v[72:75]
	v_mfma_f32_16x16x32_bf16 v[64:67], v[230:233], v[214:217], v[64:67]
	v_mfma_f32_16x16x32_bf16 v[120:123], v[226:229], v[194:197], v[120:123]
	s_waitcnt lgkmcnt(0)
	v_mfma_f32_16x16x32_bf16 v[112:115], v[234:237], v[194:197], v[112:115]
	v_mfma_f32_16x16x32_bf16 v[104:107], v[226:229], v[202:205], v[104:107]
	v_mfma_f32_16x16x32_bf16 v[96:99], v[234:237], v[202:205], v[96:99]
	v_mfma_f32_16x16x32_bf16 v[88:91], v[226:229], v[210:213], v[88:91]
	v_mfma_f32_16x16x32_bf16 v[80:83], v[234:237], v[210:213], v[80:83]
	v_mfma_f32_16x16x32_bf16 v[72:75], v[226:229], v[218:221], v[72:75]
	v_mfma_f32_16x16x32_bf16 v[64:67], v[234:237], v[218:221], v[64:67]
	s_setprio 0
	s_mov_b32 m0, s12
	v_lshl_add_u64 v[180:181], v[240:241], 0, s[86:87]
	s_barrier
	ds_read_b128 v[176:179], v163 offset:49152
	ds_read_b128 v[194:197], v163 offset:50176
	ds_read_b128 v[198:201], v163 offset:51200
	ds_read_b128 v[202:205], v163 offset:52224
	ds_read_b128 v[206:209], v163 offset:53248
	ds_read_b128 v[210:213], v163 offset:54272
	ds_read_b128 v[214:217], v163 offset:55296
	ds_read_b128 v[218:221], v163 offset:56320
	global_load_lds_dwordx4 v[180:181], off
	v_lshl_add_u64 v[180:181], v[242:243], 0, s[86:87]
	s_mov_b32 m0, s13
	s_nop 0
	global_load_lds_dwordx4 v[180:181], off
	s_barrier
	s_setprio 1
	s_waitcnt lgkmcnt(7)
	v_mfma_f32_16x16x32_bf16 v[60:63], v[138:141], v[176:179], v[60:63]
	v_mfma_f32_16x16x32_bf16 v[52:55], v[168:171], v[176:179], v[52:55]
	s_waitcnt lgkmcnt(5)
	v_mfma_f32_16x16x32_bf16 v[44:47], v[138:141], v[198:201], v[44:47]
	v_mfma_f32_16x16x32_bf16 v[36:39], v[168:171], v[198:201], v[36:39]
	s_waitcnt lgkmcnt(3)
	v_mfma_f32_16x16x32_bf16 v[28:31], v[138:141], v[206:209], v[28:31]
	v_mfma_f32_16x16x32_bf16 v[20:23], v[168:171], v[206:209], v[20:23]
	s_waitcnt lgkmcnt(1)
	v_mfma_f32_16x16x32_bf16 v[12:15], v[138:141], v[214:217], v[12:15]
	v_mfma_f32_16x16x32_bf16 v[4:7], v[168:171], v[214:217], v[4:7]
	v_mfma_f32_16x16x32_bf16 v[60:63], v[164:167], v[194:197], v[60:63]
	v_mfma_f32_16x16x32_bf16 v[52:55], v[172:175], v[194:197], v[52:55]
	v_mfma_f32_16x16x32_bf16 v[44:47], v[164:167], v[202:205], v[44:47]
	v_mfma_f32_16x16x32_bf16 v[36:39], v[172:175], v[202:205], v[36:39]
	v_mfma_f32_16x16x32_bf16 v[28:31], v[164:167], v[210:213], v[28:31]
	v_mfma_f32_16x16x32_bf16 v[20:23], v[172:175], v[210:213], v[20:23]
	s_waitcnt lgkmcnt(0)
	v_mfma_f32_16x16x32_bf16 v[12:15], v[164:167], v[218:221], v[12:15]
	v_mfma_f32_16x16x32_bf16 v[4:7], v[172:175], v[218:221], v[4:7]
	s_setprio 0
	s_barrier
	s_add_u32 s28, s28, 0x80080
	s_addc_u32 s29, s29, 0
	s_add_i32 s30, s30, s50
	v_lshl_add_u64 v[138:139], s[28:29], 0, v[144:145]
	s_mov_b32 m0, s30
	s_nop 0
	global_load_lds_dwordx4 v[138:139], off
	v_lshl_add_u64 v[138:139], s[28:29], 0, v[128:129]
	s_add_i32 m0, s30, 0x2000
	s_nop 0
	global_load_lds_dwordx4 v[138:139], off
	s_waitcnt vmcnt(6)
	s_barrier
	s_setprio 1
	v_mfma_f32_16x16x32_bf16 v[56:59], v[222:225], v[176:179], v[56:59]
	v_mfma_f32_16x16x32_bf16 v[48:51], v[230:233], v[176:179], v[48:51]
	v_mfma_f32_16x16x32_bf16 v[40:43], v[222:225], v[198:201], v[40:43]
	v_mfma_f32_16x16x32_bf16 v[32:35], v[230:233], v[198:201], v[32:35]
	v_mfma_f32_16x16x32_bf16 v[24:27], v[222:225], v[206:209], v[24:27]
	v_mfma_f32_16x16x32_bf16 v[16:19], v[230:233], v[206:209], v[16:19]
	v_mfma_f32_16x16x32_bf16 v[8:11], v[222:225], v[214:217], v[8:11]
	v_mfma_f32_16x16x32_bf16 v[0:3], v[230:233], v[214:217], v[0:3]
	v_mfma_f32_16x16x32_bf16 v[56:59], v[226:229], v[194:197], v[56:59]
	v_mfma_f32_16x16x32_bf16 v[48:51], v[234:237], v[194:197], v[48:51]
	v_mfma_f32_16x16x32_bf16 v[40:43], v[226:229], v[202:205], v[40:43]
	v_mfma_f32_16x16x32_bf16 v[32:35], v[234:237], v[202:205], v[32:35]
	v_mfma_f32_16x16x32_bf16 v[24:27], v[226:229], v[210:213], v[24:27]
	v_mfma_f32_16x16x32_bf16 v[16:19], v[234:237], v[210:213], v[16:19]
	v_mfma_f32_16x16x32_bf16 v[8:11], v[226:229], v[218:221], v[8:11]
	v_mfma_f32_16x16x32_bf16 v[0:3], v[234:237], v[218:221], v[0:3]
	s_setprio 0
	s_add_i32 s70, s70, 2
	s_add_u32 s26, s26, 0x100
	s_addc_u32 s27, s27, 0
	s_add_u32 s21, s21, 0x100
	s_addc_u32 s67, s67, 0
	s_cmp_gt_u32 s70, 29
	s_barrier
	s_cbranch_scc0 .LBB0_700
	v_pk_mul_f32 v[168:169], v[126:127], s[48:49] op_sel_hi:[1,0]
	v_pk_mul_f32 v[170:171], v[124:125], s[48:49] op_sel_hi:[1,0]
	v_exp_f32_e32 v168, v168
	v_exp_f32_e32 v170, v170
	v_exp_f32_e32 v171, v171
	v_exp_f32_e32 v169, v169
	v_pk_mul_f32 v[122:123], v[126:127], v[122:123]
	v_pk_mul_f32 v[120:121], v[124:125], v[120:121]
	v_pk_add_f32 v[170:171], v[170:171], 1.0 op_sel_hi:[1,0]
	v_pk_add_f32 v[168:169], v[168:169], 1.0 op_sel_hi:[1,0]
	v_rcp_f32_e32 v124, v170
	v_rcp_f32_e32 v125, v171
	v_rcp_f32_e32 v126, v168
	v_rcp_f32_e32 v127, v169
	v_pk_mul_f32 v[114:115], v[118:119], v[114:115]
	v_pk_mul_f32 v[120:121], v[124:125], v[120:121]
	v_pk_mul_f32 v[124:125], v[118:119], s[48:49] op_sel_hi:[1,0]
	v_pk_mul_f32 v[122:123], v[126:127], v[122:123]
	v_pk_mul_f32 v[126:127], v[116:117], s[48:49] op_sel_hi:[1,0]
	v_exp_f32_e32 v124, v124
	v_exp_f32_e32 v126, v126
	v_exp_f32_e32 v127, v127
	v_exp_f32_e32 v125, v125
	v_pk_mul_f32 v[112:113], v[116:117], v[112:113]
	v_lshl_or_b32 v140, s57, 7, v162
	v_pk_add_f32 v[126:127], v[126:127], 1.0 op_sel_hi:[1,0]
	v_pk_add_f32 v[124:125], v[124:125], 1.0 op_sel_hi:[1,0]
	v_rcp_f32_e32 v116, v126
	v_rcp_f32_e32 v117, v127
	v_rcp_f32_e32 v118, v124
	v_rcp_f32_e32 v119, v125
	v_lshl_add_u32 v164, s66, 8, v142
	v_ashrrev_i32_e32 v141, 31, v140
	v_mov_b64_e32 v[138:139], s[10:11]
	v_mad_i64_i32 v[166:167], s[26:27], v164, s90, v[138:139]
	v_lshlrev_b64 v[140:141], 1, v[140:141]
	v_pk_mul_f32 v[118:119], v[118:119], v[114:115]
	v_pk_mul_f32 v[114:115], v[116:117], v[112:113]
	v_lshl_add_u64 v[166:167], v[166:167], 0, v[140:141]
	v_cvt_pk_bf16_f32 v114, v114, v115
	v_cvt_pk_bf16_f32 v115, v118, v119
	v_cvt_pk_bf16_f32 v112, v120, v121
	v_cvt_pk_bf16_f32 v113, v122, v123
	global_store_dwordx4 v[166:167], v[112:115], off
	v_pk_mul_f32 v[116:117], v[108:109], s[48:49] op_sel_hi:[1,0]
	v_pk_mul_f32 v[106:107], v[110:111], v[106:107]
	v_pk_mul_f32 v[114:115], v[110:111], s[48:49] op_sel_hi:[1,0]
	v_exp_f32_e32 v116, v116
	v_exp_f32_e32 v117, v117
	v_exp_f32_e32 v114, v114
	v_exp_f32_e32 v115, v115
	v_pk_mul_f32 v[104:105], v[108:109], v[104:105]
	v_pk_add_f32 v[116:117], v[116:117], 1.0 op_sel_hi:[1,0]
	v_pk_mul_f32 v[98:99], v[102:103], v[98:99]
	v_pk_add_f32 v[114:115], v[114:115], 1.0 op_sel_hi:[1,0]
	v_rcp_f32_e32 v108, v116
	v_rcp_f32_e32 v109, v117
	v_rcp_f32_e32 v110, v114
	v_rcp_f32_e32 v111, v115
	v_pk_mul_f32 v[96:97], v[100:101], v[96:97]
	v_pk_mul_f32 v[104:105], v[108:109], v[104:105]
	v_pk_mul_f32 v[108:109], v[102:103], s[48:49] op_sel_hi:[1,0]
	v_pk_mul_f32 v[106:107], v[110:111], v[106:107]
	v_pk_mul_f32 v[110:111], v[100:101], s[48:49] op_sel_hi:[1,0]
	v_exp_f32_e32 v108, v108
	v_exp_f32_e32 v110, v110
	v_exp_f32_e32 v111, v111
	v_exp_f32_e32 v109, v109
	v_or_b32_e32 v112, 16, v164
	v_mad_i64_i32 v[112:113], s[26:27], v112, s90, v[138:139]
	v_pk_add_f32 v[108:109], v[108:109], 1.0 op_sel_hi:[1,0]
	v_pk_add_f32 v[110:111], v[110:111], 1.0 op_sel_hi:[1,0]
	v_rcp_f32_e32 v102, v108
	v_rcp_f32_e32 v100, v110
	v_rcp_f32_e32 v101, v111
	v_rcp_f32_e32 v103, v109
	v_lshl_add_u64 v[112:113], v[112:113], 0, v[140:141]
	v_pk_mul_f32 v[90:91], v[94:95], v[90:91]
	v_pk_mul_f32 v[88:89], v[92:93], v[88:89]
	v_pk_mul_f32 v[102:103], v[102:103], v[98:99]
	v_pk_mul_f32 v[98:99], v[100:101], v[96:97]
	v_cvt_pk_bf16_f32 v96, v104, v105
	v_cvt_pk_bf16_f32 v97, v106, v107
	v_pk_mul_f32 v[100:101], v[92:93], s[48:49] op_sel_hi:[1,0]
	v_cvt_pk_bf16_f32 v98, v98, v99
	v_cvt_pk_bf16_f32 v99, v102, v103
	global_store_dwordx4 v[112:113], v[96:99], off
	v_exp_f32_e32 v100, v100
	v_exp_f32_e32 v101, v101
	v_pk_mul_f32 v[98:99], v[94:95], s[48:49] op_sel_hi:[1,0]
	v_pk_mul_f32 v[82:83], v[86:87], v[82:83]
	v_exp_f32_e32 v98, v98
	v_exp_f32_e32 v99, v99
	v_pk_add_f32 v[100:101], v[100:101], 1.0 op_sel_hi:[1,0]
	v_pk_mul_f32 v[80:81], v[84:85], v[80:81]
	v_rcp_f32_e32 v92, v100
	v_pk_add_f32 v[98:99], v[98:99], 1.0 op_sel_hi:[1,0]
	v_rcp_f32_e32 v93, v101
	v_rcp_f32_e32 v94, v98
	v_rcp_f32_e32 v95, v99
	v_or_b32_e32 v96, 32, v164
	v_pk_mul_f32 v[88:89], v[92:93], v[88:89]
	v_pk_mul_f32 v[92:93], v[86:87], s[48:49] op_sel_hi:[1,0]
	v_pk_mul_f32 v[90:91], v[94:95], v[90:91]
	v_pk_mul_f32 v[94:95], v[84:85], s[48:49] op_sel_hi:[1,0]
	v_exp_f32_e32 v92, v92
	v_exp_f32_e32 v94, v94
	v_exp_f32_e32 v95, v95
	v_exp_f32_e32 v93, v93
	v_mad_i64_i32 v[96:97], s[26:27], v96, s90, v[138:139]
	v_pk_add_f32 v[94:95], v[94:95], 1.0 op_sel_hi:[1,0]
	v_pk_add_f32 v[92:93], v[92:93], 1.0 op_sel_hi:[1,0]
	v_rcp_f32_e32 v84, v94
	v_rcp_f32_e32 v85, v95
	v_rcp_f32_e32 v86, v92
	v_rcp_f32_e32 v87, v93
	v_lshl_add_u64 v[96:97], v[96:97], 0, v[140:141]
	v_pk_mul_f32 v[74:75], v[78:79], v[74:75]
	v_pk_mul_f32 v[72:73], v[76:77], v[72:73]
	v_pk_mul_f32 v[86:87], v[86:87], v[82:83]
	v_pk_mul_f32 v[82:83], v[84:85], v[80:81]
	v_cvt_pk_bf16_f32 v80, v88, v89
	v_cvt_pk_bf16_f32 v81, v90, v91
	v_pk_mul_f32 v[84:85], v[76:77], s[48:49] op_sel_hi:[1,0]
	v_cvt_pk_bf16_f32 v82, v82, v83
	v_cvt_pk_bf16_f32 v83, v86, v87
	global_store_dwordx4 v[96:97], v[80:83], off
	v_exp_f32_e32 v84, v84
	v_exp_f32_e32 v85, v85
	v_pk_mul_f32 v[82:83], v[78:79], s[48:49] op_sel_hi:[1,0]
	v_pk_mul_f32 v[66:67], v[70:71], v[66:67]
	v_exp_f32_e32 v82, v82
	v_exp_f32_e32 v83, v83
	v_pk_add_f32 v[84:85], v[84:85], 1.0 op_sel_hi:[1,0]
	v_pk_mul_f32 v[64:65], v[68:69], v[64:65]
	v_rcp_f32_e32 v76, v84
	v_pk_add_f32 v[82:83], v[82:83], 1.0 op_sel_hi:[1,0]
	v_rcp_f32_e32 v77, v85
	v_rcp_f32_e32 v78, v82
	v_rcp_f32_e32 v79, v83
	v_or_b32_e32 v80, 48, v164
	v_pk_mul_f32 v[72:73], v[76:77], v[72:73]
	v_pk_mul_f32 v[76:77], v[70:71], s[48:49] op_sel_hi:[1,0]
	v_pk_mul_f32 v[74:75], v[78:79], v[74:75]
	v_pk_mul_f32 v[78:79], v[68:69], s[48:49] op_sel_hi:[1,0]
	v_exp_f32_e32 v76, v76
	v_exp_f32_e32 v78, v78
	v_exp_f32_e32 v79, v79
	v_exp_f32_e32 v77, v77
	v_mad_i64_i32 v[80:81], s[26:27], v80, s90, v[138:139]
	v_pk_add_f32 v[78:79], v[78:79], 1.0 op_sel_hi:[1,0]
	v_pk_add_f32 v[76:77], v[76:77], 1.0 op_sel_hi:[1,0]
	v_rcp_f32_e32 v68, v78
	v_rcp_f32_e32 v69, v79
	v_rcp_f32_e32 v70, v76
	v_rcp_f32_e32 v71, v77
	v_lshl_add_u64 v[80:81], v[80:81], 0, v[140:141]
	v_pk_mul_f32 v[58:59], v[62:63], v[58:59]
	v_pk_mul_f32 v[56:57], v[60:61], v[56:57]
	v_pk_mul_f32 v[70:71], v[70:71], v[66:67]
	v_pk_mul_f32 v[66:67], v[68:69], v[64:65]
	v_cvt_pk_bf16_f32 v64, v72, v73
	v_cvt_pk_bf16_f32 v65, v74, v75
	v_pk_mul_f32 v[68:69], v[60:61], s[48:49] op_sel_hi:[1,0]
	v_cvt_pk_bf16_f32 v66, v66, v67
	v_cvt_pk_bf16_f32 v67, v70, v71
	global_store_dwordx4 v[80:81], v[64:67], off
	v_exp_f32_e32 v68, v68
	v_exp_f32_e32 v69, v69
	v_pk_mul_f32 v[66:67], v[62:63], s[48:49] op_sel_hi:[1,0]
	v_pk_mul_f32 v[50:51], v[54:55], v[50:51]
	v_exp_f32_e32 v66, v66
	v_exp_f32_e32 v67, v67
	v_pk_add_f32 v[68:69], v[68:69], 1.0 op_sel_hi:[1,0]
	v_pk_mul_f32 v[48:49], v[52:53], v[48:49]
	v_rcp_f32_e32 v60, v68
	v_pk_add_f32 v[66:67], v[66:67], 1.0 op_sel_hi:[1,0]
	v_rcp_f32_e32 v61, v69
	v_rcp_f32_e32 v62, v66
	v_rcp_f32_e32 v63, v67
	v_add_u32_e32 v64, 0x80, v164
	v_pk_mul_f32 v[56:57], v[60:61], v[56:57]
	v_pk_mul_f32 v[60:61], v[54:55], s[48:49] op_sel_hi:[1,0]
	v_pk_mul_f32 v[58:59], v[62:63], v[58:59]
	v_pk_mul_f32 v[62:63], v[52:53], s[48:49] op_sel_hi:[1,0]
	v_exp_f32_e32 v60, v60
	v_exp_f32_e32 v62, v62
	v_exp_f32_e32 v63, v63
	v_exp_f32_e32 v61, v61
	v_mad_i64_i32 v[64:65], s[26:27], v64, s90, v[138:139]
	v_pk_add_f32 v[62:63], v[62:63], 1.0 op_sel_hi:[1,0]
	v_pk_add_f32 v[60:61], v[60:61], 1.0 op_sel_hi:[1,0]
	v_rcp_f32_e32 v52, v62
	v_rcp_f32_e32 v53, v63
	v_rcp_f32_e32 v54, v60
	v_rcp_f32_e32 v55, v61
	v_lshl_add_u64 v[64:65], v[64:65], 0, v[140:141]
	v_pk_mul_f32 v[42:43], v[46:47], v[42:43]
	v_pk_mul_f32 v[40:41], v[44:45], v[40:41]
	v_pk_mul_f32 v[54:55], v[54:55], v[50:51]
	v_pk_mul_f32 v[50:51], v[52:53], v[48:49]
	v_cvt_pk_bf16_f32 v48, v56, v57
	v_cvt_pk_bf16_f32 v49, v58, v59
	v_pk_mul_f32 v[52:53], v[44:45], s[48:49] op_sel_hi:[1,0]
	v_cvt_pk_bf16_f32 v50, v50, v51
	v_cvt_pk_bf16_f32 v51, v54, v55
	global_store_dwordx4 v[64:65], v[48:51], off
	v_exp_f32_e32 v52, v52
	v_exp_f32_e32 v53, v53
	v_pk_mul_f32 v[50:51], v[46:47], s[48:49] op_sel_hi:[1,0]
	v_pk_mul_f32 v[34:35], v[38:39], v[34:35]
	v_exp_f32_e32 v50, v50
	v_exp_f32_e32 v51, v51
	v_pk_add_f32 v[52:53], v[52:53], 1.0 op_sel_hi:[1,0]
	v_pk_mul_f32 v[32:33], v[36:37], v[32:33]
	v_rcp_f32_e32 v44, v52
	v_pk_add_f32 v[50:51], v[50:51], 1.0 op_sel_hi:[1,0]
	v_rcp_f32_e32 v45, v53
	v_rcp_f32_e32 v46, v50
	v_rcp_f32_e32 v47, v51
	v_add_u32_e32 v48, 0x90, v164
	v_pk_mul_f32 v[40:41], v[44:45], v[40:41]
	v_pk_mul_f32 v[44:45], v[38:39], s[48:49] op_sel_hi:[1,0]
	v_pk_mul_f32 v[42:43], v[46:47], v[42:43]
	v_pk_mul_f32 v[46:47], v[36:37], s[48:49] op_sel_hi:[1,0]
	v_exp_f32_e32 v44, v44
	v_exp_f32_e32 v46, v46
	v_exp_f32_e32 v47, v47
	v_exp_f32_e32 v45, v45
	v_mad_i64_i32 v[48:49], s[26:27], v48, s90, v[138:139]
	v_pk_add_f32 v[46:47], v[46:47], 1.0 op_sel_hi:[1,0]
	v_pk_add_f32 v[44:45], v[44:45], 1.0 op_sel_hi:[1,0]
	v_rcp_f32_e32 v36, v46
	v_rcp_f32_e32 v37, v47
	v_rcp_f32_e32 v38, v44
	v_rcp_f32_e32 v39, v45
	v_lshl_add_u64 v[48:49], v[48:49], 0, v[140:141]
	v_pk_mul_f32 v[26:27], v[30:31], v[26:27]
	v_pk_mul_f32 v[24:25], v[28:29], v[24:25]
	v_pk_mul_f32 v[38:39], v[38:39], v[34:35]
	v_pk_mul_f32 v[34:35], v[36:37], v[32:33]
	v_cvt_pk_bf16_f32 v32, v40, v41
	v_cvt_pk_bf16_f32 v33, v42, v43
	v_pk_mul_f32 v[36:37], v[28:29], s[48:49] op_sel_hi:[1,0]
	v_cvt_pk_bf16_f32 v34, v34, v35
	v_cvt_pk_bf16_f32 v35, v38, v39
	global_store_dwordx4 v[48:49], v[32:35], off
	v_exp_f32_e32 v36, v36
	v_exp_f32_e32 v37, v37
	v_pk_mul_f32 v[34:35], v[30:31], s[48:49] op_sel_hi:[1,0]
	v_pk_mul_f32 v[18:19], v[22:23], v[18:19]
	v_exp_f32_e32 v34, v34
	v_exp_f32_e32 v35, v35
	v_pk_add_f32 v[36:37], v[36:37], 1.0 op_sel_hi:[1,0]
	v_pk_mul_f32 v[16:17], v[20:21], v[16:17]
	v_rcp_f32_e32 v28, v36
	v_pk_add_f32 v[34:35], v[34:35], 1.0 op_sel_hi:[1,0]
	v_rcp_f32_e32 v29, v37
	v_rcp_f32_e32 v30, v34
	v_rcp_f32_e32 v31, v35
	v_add_u32_e32 v32, 0xa0, v164
	v_pk_mul_f32 v[24:25], v[28:29], v[24:25]
	v_pk_mul_f32 v[28:29], v[22:23], s[48:49] op_sel_hi:[1,0]
	v_pk_mul_f32 v[26:27], v[30:31], v[26:27]
	v_pk_mul_f32 v[30:31], v[20:21], s[48:49] op_sel_hi:[1,0]
	v_exp_f32_e32 v28, v28
	v_exp_f32_e32 v30, v30
	v_exp_f32_e32 v31, v31
	v_exp_f32_e32 v29, v29
	v_mad_i64_i32 v[32:33], s[26:27], v32, s90, v[138:139]
	v_pk_add_f32 v[30:31], v[30:31], 1.0 op_sel_hi:[1,0]
	v_pk_add_f32 v[28:29], v[28:29], 1.0 op_sel_hi:[1,0]
	v_rcp_f32_e32 v20, v30
	v_rcp_f32_e32 v21, v31
	v_rcp_f32_e32 v22, v28
	v_rcp_f32_e32 v23, v29
	v_lshl_add_u64 v[32:33], v[32:33], 0, v[140:141]
	v_pk_mul_f32 v[10:11], v[14:15], v[10:11]
	v_pk_mul_f32 v[8:9], v[12:13], v[8:9]
	v_pk_mul_f32 v[22:23], v[22:23], v[18:19]
	v_pk_mul_f32 v[18:19], v[20:21], v[16:17]
	v_cvt_pk_bf16_f32 v16, v24, v25
	v_cvt_pk_bf16_f32 v17, v26, v27
	v_pk_mul_f32 v[20:21], v[12:13], s[48:49] op_sel_hi:[1,0]
	v_cvt_pk_bf16_f32 v18, v18, v19
	v_cvt_pk_bf16_f32 v19, v22, v23
	global_store_dwordx4 v[32:33], v[16:19], off
	v_exp_f32_e32 v20, v20
	v_exp_f32_e32 v21, v21
	v_pk_mul_f32 v[18:19], v[14:15], s[48:49] op_sel_hi:[1,0]
	v_pk_mul_f32 v[2:3], v[6:7], v[2:3]
	v_exp_f32_e32 v18, v18
	v_exp_f32_e32 v19, v19
	v_pk_add_f32 v[20:21], v[20:21], 1.0 op_sel_hi:[1,0]
	v_pk_mul_f32 v[0:1], v[4:5], v[0:1]
	v_rcp_f32_e32 v12, v20
	v_pk_add_f32 v[18:19], v[18:19], 1.0 op_sel_hi:[1,0]
	v_rcp_f32_e32 v13, v21
	v_rcp_f32_e32 v14, v18
	v_rcp_f32_e32 v15, v19
	v_add_u32_e32 v16, 0xb0, v164
	v_pk_mul_f32 v[8:9], v[12:13], v[8:9]
	v_pk_mul_f32 v[12:13], v[6:7], s[48:49] op_sel_hi:[1,0]
	v_pk_mul_f32 v[10:11], v[14:15], v[10:11]
	v_pk_mul_f32 v[14:15], v[4:5], s[48:49] op_sel_hi:[1,0]
	v_exp_f32_e32 v12, v12
	v_exp_f32_e32 v14, v14
	v_exp_f32_e32 v15, v15
	v_exp_f32_e32 v13, v13
	v_mad_i64_i32 v[16:17], s[26:27], v16, s90, v[138:139]
	v_pk_add_f32 v[14:15], v[14:15], 1.0 op_sel_hi:[1,0]
	v_pk_add_f32 v[12:13], v[12:13], 1.0 op_sel_hi:[1,0]
	v_rcp_f32_e32 v4, v14
	v_rcp_f32_e32 v5, v15
	v_rcp_f32_e32 v6, v12
	v_rcp_f32_e32 v7, v13
	v_lshl_add_u64 v[16:17], v[16:17], 0, v[140:141]
	s_and_b64 vcc, exec, s[4:5]
	s_mov_b32 s57, s56
	v_pk_mul_f32 v[6:7], v[6:7], v[2:3]
	v_pk_mul_f32 v[2:3], v[4:5], v[0:1]
	s_mov_b32 s66, s20
	s_mov_b64 s[28:29], s[8:9]
	s_mov_b64 s[26:27], s[6:7]
	v_cvt_pk_bf16_f32 v0, v8, v9
	v_cvt_pk_bf16_f32 v1, v10, v11
	v_cvt_pk_bf16_f32 v2, v2, v3
	v_cvt_pk_bf16_f32 v3, v6, v7
	global_store_dwordx4 v[16:17], v[0:3], off
	s_cbranch_vccz .LBB0_693
	s_waitcnt vmcnt(0)
	s_cmpk_gt_u32 s18, 0xff
	s_mov_b32 s55, 0xbc00000
	s_cbranch_scc1 .LBB0_704
	s_barrier

.LBB0_773:
	s_add_i32 s83, s28, 2
	s_add_u32 s30, s16, 0x80
	s_addc_u32 s29, s17, 0
	s_add_i32 s88, 0, 0x10000
	v_add_u32_e32 v138, s88, v141
	ds_read_b128 v[162:165], v138
	ds_read_b128 v[166:169], v138 offset:1024
	ds_read_b128 v[170:173], v138 offset:2048
	ds_read_b128 v[174:177], v138 offset:3072
	s_cmp_eq_u32 s67, s28
	s_cselect_b32 s28, s6, s30
	s_cselect_b32 s29, s7, s29
	s_cselect_b32 s31, s9, s82
	s_cselect_b32 s30, s8, s75
	v_lshl_add_u64 v[138:139], s[16:17], 0, v[134:135]
	s_add_i32 m0, s37, 0xc000
	ds_read_b128 v[178:181], v143
	ds_read_b128 v[194:197], v143 offset:1024
	ds_read_b128 v[198:201], v143 offset:2048
	ds_read_b128 v[202:205], v143 offset:3072
	ds_read_b128 v[206:209], v143 offset:4096
	ds_read_b128 v[210:213], v143 offset:5120
	ds_read_b128 v[214:217], v143 offset:6144
	ds_read_b128 v[218:221], v143 offset:7168
	global_load_lds_dwordx4 v[138:139], off
	v_lshl_add_u64 v[138:139], s[16:17], 0, v[136:137]
	s_add_i32 m0, s37, 0xe000
	s_nop 0
	global_load_lds_dwordx4 v[138:139], off
	s_waitcnt lgkmcnt(8)
	s_barrier
	s_setprio 1
	s_waitcnt lgkmcnt(7)
	v_mfma_f32_16x16x32_bf16 v[124:127], v[162:165], v[178:181], v[124:127]
	v_mfma_f32_16x16x32_bf16 v[120:123], v[170:173], v[178:181], v[120:123]
	s_waitcnt lgkmcnt(5)
	v_mfma_f32_16x16x32_bf16 v[116:119], v[162:165], v[198:201], v[116:119]
	v_mfma_f32_16x16x32_bf16 v[108:111], v[170:173], v[198:201], v[108:111]
	s_waitcnt lgkmcnt(3)
	v_mfma_f32_16x16x32_bf16 v[100:103], v[162:165], v[206:209], v[100:103]
	v_mfma_f32_16x16x32_bf16 v[92:95], v[170:173], v[206:209], v[92:95]
	s_waitcnt lgkmcnt(1)
	v_mfma_f32_16x16x32_bf16 v[84:87], v[162:165], v[214:217], v[84:87]
	v_mfma_f32_16x16x32_bf16 v[76:79], v[170:173], v[214:217], v[76:79]
	v_mfma_f32_16x16x32_bf16 v[124:127], v[166:169], v[194:197], v[124:127]
	v_mfma_f32_16x16x32_bf16 v[120:123], v[174:177], v[194:197], v[120:123]
	v_mfma_f32_16x16x32_bf16 v[116:119], v[166:169], v[202:205], v[116:119]
	v_mfma_f32_16x16x32_bf16 v[108:111], v[174:177], v[202:205], v[108:111]
	v_mfma_f32_16x16x32_bf16 v[100:103], v[166:169], v[210:213], v[100:103]
	v_mfma_f32_16x16x32_bf16 v[92:95], v[174:177], v[210:213], v[92:95]
	s_waitcnt lgkmcnt(0)
	v_mfma_f32_16x16x32_bf16 v[84:87], v[166:169], v[218:221], v[84:87]
	v_mfma_f32_16x16x32_bf16 v[76:79], v[174:177], v[218:221], v[76:79]
	s_setprio 0
	s_barrier
	s_add_i32 s89, 0, 0x14000
	v_add_u32_e32 v138, s89, v141
	s_add_i32 s88, s88, s36
	ds_read_b128 v[222:225], v138
	ds_read_b128 v[226:229], v138 offset:1024
	ds_read_b128 v[230:233], v138 offset:2048
	ds_read_b128 v[234:237], v138 offset:3072
	v_lshl_add_u64 v[138:139], s[30:31], 0, v[144:145]
	s_mov_b32 m0, s88
	v_lshl_add_u64 v[238:239], s[30:31], 0, v[128:129]
	global_load_lds_dwordx4 v[138:139], off
	s_add_i32 m0, s88, 0x2000
	s_nop 0
	global_load_lds_dwordx4 v[238:239], off
	s_barrier
	s_setprio 1
	s_waitcnt lgkmcnt(3)
	v_mfma_f32_16x16x32_bf16 v[112:115], v[222:225], v[178:181], v[112:115]
	s_waitcnt lgkmcnt(1)
	v_mfma_f32_16x16x32_bf16 v[104:107], v[230:233], v[178:181], v[104:107]
	v_mfma_f32_16x16x32_bf16 v[96:99], v[222:225], v[198:201], v[96:99]
	v_mfma_f32_16x16x32_bf16 v[88:91], v[230:233], v[198:201], v[88:91]
	v_mfma_f32_16x16x32_bf16 v[80:83], v[222:225], v[206:209], v[80:83]
	v_mfma_f32_16x16x32_bf16 v[72:75], v[230:233], v[206:209], v[72:75]
	v_mfma_f32_16x16x32_bf16 v[68:71], v[222:225], v[214:217], v[68:71]
	v_mfma_f32_16x16x32_bf16 v[64:67], v[230:233], v[214:217], v[64:67]
	v_mfma_f32_16x16x32_bf16 v[112:115], v[226:229], v[194:197], v[112:115]
	s_waitcnt lgkmcnt(0)
	v_mfma_f32_16x16x32_bf16 v[104:107], v[234:237], v[194:197], v[104:107]
	v_mfma_f32_16x16x32_bf16 v[96:99], v[226:229], v[202:205], v[96:99]
	v_mfma_f32_16x16x32_bf16 v[88:91], v[234:237], v[202:205], v[88:91]
	v_mfma_f32_16x16x32_bf16 v[80:83], v[226:229], v[210:213], v[80:83]
	v_mfma_f32_16x16x32_bf16 v[72:75], v[234:237], v[210:213], v[72:75]
	v_mfma_f32_16x16x32_bf16 v[68:71], v[226:229], v[218:221], v[68:71]
	v_mfma_f32_16x16x32_bf16 v[64:67], v[234:237], v[218:221], v[64:67]
	s_setprio 0
	s_mov_b32 m0, s37
	v_lshl_add_u64 v[240:241], s[28:29], 0, v[132:133]
	s_barrier
	ds_read_b128 v[178:181], v143 offset:16384
	ds_read_b128 v[194:197], v143 offset:17408
	ds_read_b128 v[198:201], v143 offset:18432
	ds_read_b128 v[202:205], v143 offset:19456
	ds_read_b128 v[206:209], v143 offset:20480
	ds_read_b128 v[210:213], v143 offset:21504
	ds_read_b128 v[214:217], v143 offset:22528
	ds_read_b128 v[218:221], v143 offset:23552
	global_load_lds_dwordx4 v[240:241], off
	v_lshl_add_u64 v[242:243], s[28:29], 0, v[130:131]
	s_mov_b32 m0, s50
	s_nop 0
	global_load_lds_dwordx4 v[242:243], off
	s_barrier
	s_setprio 1
	s_waitcnt lgkmcnt(7)
	v_mfma_f32_16x16x32_bf16 v[60:63], v[162:165], v[178:181], v[60:63]
	v_mfma_f32_16x16x32_bf16 v[56:59], v[170:173], v[178:181], v[56:59]
	s_waitcnt lgkmcnt(5)
	v_mfma_f32_16x16x32_bf16 v[52:55], v[162:165], v[198:201], v[52:55]
	v_mfma_f32_16x16x32_bf16 v[48:51], v[170:173], v[198:201], v[48:51]
	s_waitcnt lgkmcnt(3)
	v_mfma_f32_16x16x32_bf16 v[36:39], v[162:165], v[206:209], v[36:39]
	v_mfma_f32_16x16x32_bf16 v[32:35], v[170:173], v[206:209], v[32:35]
	s_waitcnt lgkmcnt(1)
	v_mfma_f32_16x16x32_bf16 v[20:23], v[162:165], v[214:217], v[20:23]
	v_mfma_f32_16x16x32_bf16 v[16:19], v[170:173], v[214:217], v[16:19]
	v_mfma_f32_16x16x32_bf16 v[60:63], v[166:169], v[194:197], v[60:63]
	v_mfma_f32_16x16x32_bf16 v[56:59], v[174:177], v[194:197], v[56:59]
	v_mfma_f32_16x16x32_bf16 v[52:55], v[166:169], v[202:205], v[52:55]
	v_mfma_f32_16x16x32_bf16 v[48:51], v[174:177], v[202:205], v[48:51]
	v_mfma_f32_16x16x32_bf16 v[36:39], v[166:169], v[210:213], v[36:39]
	v_mfma_f32_16x16x32_bf16 v[32:35], v[174:177], v[210:213], v[32:35]
	s_waitcnt lgkmcnt(0)
	v_mfma_f32_16x16x32_bf16 v[20:23], v[166:169], v[218:221], v[20:23]
	v_mfma_f32_16x16x32_bf16 v[16:19], v[174:177], v[218:221], v[16:19]
	s_setprio 0
	s_barrier
	s_add_u32 s30, s30, s76
	s_addc_u32 s31, s31, 0
	s_add_i32 s88, s89, s36
	v_lshl_add_u64 v[244:245], s[30:31], 0, v[144:145]
	s_mov_b32 m0, s88
	v_lshl_add_u64 v[246:247], s[30:31], 0, v[128:129]
	global_load_lds_dwordx4 v[244:245], off
	s_add_i32 m0, s88, 0x2000
	s_nop 0
	global_load_lds_dwordx4 v[246:247], off
	s_waitcnt vmcnt(6)
	s_barrier
	s_setprio 1
	v_mfma_f32_16x16x32_bf16 v[44:47], v[222:225], v[178:181], v[44:47]
	v_mfma_f32_16x16x32_bf16 v[40:43], v[230:233], v[178:181], v[40:43]
	v_mfma_f32_16x16x32_bf16 v[28:31], v[222:225], v[198:201], v[28:31]
	v_mfma_f32_16x16x32_bf16 v[24:27], v[230:233], v[198:201], v[24:27]
	v_mfma_f32_16x16x32_bf16 v[12:15], v[222:225], v[206:209], v[12:15]
	v_mfma_f32_16x16x32_bf16 v[8:11], v[230:233], v[206:209], v[8:11]
	v_mfma_f32_16x16x32_bf16 v[4:7], v[222:225], v[214:217], v[4:7]
	v_mfma_f32_16x16x32_bf16 v[0:3], v[230:233], v[214:217], v[0:3]
	v_mfma_f32_16x16x32_bf16 v[44:47], v[226:229], v[194:197], v[44:47]
	v_mfma_f32_16x16x32_bf16 v[40:43], v[234:237], v[194:197], v[40:43]
	v_mfma_f32_16x16x32_bf16 v[28:31], v[226:229], v[202:205], v[28:31]
	v_mfma_f32_16x16x32_bf16 v[24:27], v[234:237], v[202:205], v[24:27]
	v_mfma_f32_16x16x32_bf16 v[12:15], v[226:229], v[210:213], v[12:15]
	v_mfma_f32_16x16x32_bf16 v[8:11], v[234:237], v[210:213], v[8:11]
	v_mfma_f32_16x16x32_bf16 v[4:7], v[226:229], v[218:221], v[4:7]
	v_mfma_f32_16x16x32_bf16 v[0:3], v[234:237], v[218:221], v[0:3]
	s_setprio 0
	s_add_i32 s30, 0, 0x18000
	v_add_u32_e32 v174, s30, v141
	s_barrier
	ds_read_b128 v[162:165], v174
	ds_read_b128 v[166:169], v174 offset:1024
	ds_read_b128 v[170:173], v174 offset:2048
	ds_read_b128 v[174:177], v174 offset:3072
	s_add_u32 s28, s28, s76
	s_addc_u32 s29, s29, 0
	s_mov_b32 m0, s51
	v_lshl_add_u64 v[222:223], s[28:29], 0, v[132:133]
	ds_read_b128 v[178:181], v143 offset:32768
	ds_read_b128 v[194:197], v143 offset:33792
	ds_read_b128 v[198:201], v143 offset:34816
	ds_read_b128 v[202:205], v143 offset:35840
	ds_read_b128 v[206:209], v143 offset:36864
	ds_read_b128 v[210:213], v143 offset:37888
	ds_read_b128 v[214:217], v143 offset:38912
	ds_read_b128 v[218:221], v143 offset:39936
	global_load_lds_dwordx4 v[222:223], off
	v_lshl_add_u64 v[222:223], s[28:29], 0, v[130:131]
	s_mov_b32 m0, s54
	s_nop 0
	global_load_lds_dwordx4 v[222:223], off
	s_waitcnt lgkmcnt(8)
	s_barrier
	s_setprio 1
	s_waitcnt lgkmcnt(7)
	v_mfma_f32_16x16x32_bf16 v[124:127], v[162:165], v[178:181], v[124:127]
	v_mfma_f32_16x16x32_bf16 v[120:123], v[170:173], v[178:181], v[120:123]
	s_waitcnt lgkmcnt(5)
	v_mfma_f32_16x16x32_bf16 v[116:119], v[162:165], v[198:201], v[116:119]
	v_mfma_f32_16x16x32_bf16 v[108:111], v[170:173], v[198:201], v[108:111]
	s_waitcnt lgkmcnt(3)
	v_mfma_f32_16x16x32_bf16 v[100:103], v[162:165], v[206:209], v[100:103]
	v_mfma_f32_16x16x32_bf16 v[92:95], v[170:173], v[206:209], v[92:95]
	s_waitcnt lgkmcnt(1)
	v_mfma_f32_16x16x32_bf16 v[84:87], v[162:165], v[214:217], v[84:87]
	v_mfma_f32_16x16x32_bf16 v[76:79], v[170:173], v[214:217], v[76:79]
	v_mfma_f32_16x16x32_bf16 v[124:127], v[166:169], v[194:197], v[124:127]
	v_mfma_f32_16x16x32_bf16 v[120:123], v[174:177], v[194:197], v[120:123]
	v_mfma_f32_16x16x32_bf16 v[116:119], v[166:169], v[202:205], v[116:119]
	v_mfma_f32_16x16x32_bf16 v[108:111], v[174:177], v[202:205], v[108:111]
	v_mfma_f32_16x16x32_bf16 v[100:103], v[166:169], v[210:213], v[100:103]
	v_mfma_f32_16x16x32_bf16 v[92:95], v[174:177], v[210:213], v[92:95]
	s_waitcnt lgkmcnt(0)
	v_mfma_f32_16x16x32_bf16 v[84:87], v[166:169], v[218:221], v[84:87]
	v_mfma_f32_16x16x32_bf16 v[76:79], v[174:177], v[218:221], v[76:79]
	s_setprio 0
	s_barrier
	s_add_i32 s28, 0, 0x1c000
	s_add_i32 s29, s30, s36
	v_add_u32_e32 v193, s28, v141
	v_lshl_add_u64 v[138:139], v[138:139], 0, s[86:87]
	s_mov_b32 m0, s29
	ds_read_b128 v[222:225], v193
	ds_read_b128 v[226:229], v193 offset:1024
	ds_read_b128 v[230:233], v193 offset:2048
	ds_read_b128 v[234:237], v193 offset:3072
	global_load_lds_dwordx4 v[138:139], off
	v_lshl_add_u64 v[138:139], v[238:239], 0, s[86:87]
	s_add_i32 m0, s29, 0x2000
	s_nop 0
	global_load_lds_dwordx4 v[138:139], off
	s_barrier
	s_setprio 1
	s_waitcnt lgkmcnt(3)
	v_mfma_f32_16x16x32_bf16 v[112:115], v[222:225], v[178:181], v[112:115]
	s_waitcnt lgkmcnt(1)
	v_mfma_f32_16x16x32_bf16 v[104:107], v[230:233], v[178:181], v[104:107]
	v_mfma_f32_16x16x32_bf16 v[96:99], v[222:225], v[198:201], v[96:99]
	v_mfma_f32_16x16x32_bf16 v[88:91], v[230:233], v[198:201], v[88:91]
	v_mfma_f32_16x16x32_bf16 v[80:83], v[222:225], v[206:209], v[80:83]
	v_mfma_f32_16x16x32_bf16 v[72:75], v[230:233], v[206:209], v[72:75]
	v_mfma_f32_16x16x32_bf16 v[68:71], v[222:225], v[214:217], v[68:71]
	v_mfma_f32_16x16x32_bf16 v[64:67], v[230:233], v[214:217], v[64:67]
	v_mfma_f32_16x16x32_bf16 v[112:115], v[226:229], v[194:197], v[112:115]
	s_waitcnt lgkmcnt(0)
	v_mfma_f32_16x16x32_bf16 v[104:107], v[234:237], v[194:197], v[104:107]
	v_mfma_f32_16x16x32_bf16 v[96:99], v[226:229], v[202:205], v[96:99]
	v_mfma_f32_16x16x32_bf16 v[88:91], v[234:237], v[202:205], v[88:91]
	v_mfma_f32_16x16x32_bf16 v[80:83], v[226:229], v[210:213], v[80:83]
	v_mfma_f32_16x16x32_bf16 v[72:75], v[234:237], v[210:213], v[72:75]
	v_mfma_f32_16x16x32_bf16 v[68:71], v[226:229], v[218:221], v[68:71]
	v_mfma_f32_16x16x32_bf16 v[64:67], v[234:237], v[218:221], v[64:67]
	s_setprio 0
	s_mov_b32 m0, s57
	v_lshl_add_u64 v[138:139], v[240:241], 0, s[86:87]
	s_barrier
	ds_read_b128 v[178:181], v143 offset:49152
	ds_read_b128 v[194:197], v143 offset:50176
	ds_read_b128 v[198:201], v143 offset:51200
	ds_read_b128 v[202:205], v143 offset:52224
	ds_read_b128 v[206:209], v143 offset:53248
	ds_read_b128 v[210:213], v143 offset:54272
	ds_read_b128 v[214:217], v143 offset:55296
	ds_read_b128 v[218:221], v143 offset:56320
	global_load_lds_dwordx4 v[138:139], off
	v_lshl_add_u64 v[138:139], v[242:243], 0, s[86:87]
	s_mov_b32 m0, s66
	s_nop 0
	global_load_lds_dwordx4 v[138:139], off
	s_barrier
	s_setprio 1
	s_waitcnt lgkmcnt(7)
	v_mfma_f32_16x16x32_bf16 v[60:63], v[162:165], v[178:181], v[60:63]
	v_mfma_f32_16x16x32_bf16 v[56:59], v[170:173], v[178:181], v[56:59]
	s_waitcnt lgkmcnt(5)
	v_mfma_f32_16x16x32_bf16 v[52:55], v[162:165], v[198:201], v[52:55]
	v_mfma_f32_16x16x32_bf16 v[48:51], v[170:173], v[198:201], v[48:51]
	s_waitcnt lgkmcnt(3)
	v_mfma_f32_16x16x32_bf16 v[36:39], v[162:165], v[206:209], v[36:39]
	v_mfma_f32_16x16x32_bf16 v[32:35], v[170:173], v[206:209], v[32:35]
	s_waitcnt lgkmcnt(1)
	v_mfma_f32_16x16x32_bf16 v[20:23], v[162:165], v[214:217], v[20:23]
	v_mfma_f32_16x16x32_bf16 v[16:19], v[170:173], v[214:217], v[16:19]
	v_mfma_f32_16x16x32_bf16 v[60:63], v[166:169], v[194:197], v[60:63]
	v_mfma_f32_16x16x32_bf16 v[56:59], v[174:177], v[194:197], v[56:59]
	v_mfma_f32_16x16x32_bf16 v[52:55], v[166:169], v[202:205], v[52:55]
	v_mfma_f32_16x16x32_bf16 v[48:51], v[174:177], v[202:205], v[48:51]
	v_mfma_f32_16x16x32_bf16 v[36:39], v[166:169], v[210:213], v[36:39]
	v_mfma_f32_16x16x32_bf16 v[32:35], v[174:177], v[210:213], v[32:35]
	s_waitcnt lgkmcnt(0)
	v_mfma_f32_16x16x32_bf16 v[20:23], v[166:169], v[218:221], v[20:23]
	v_mfma_f32_16x16x32_bf16 v[16:19], v[174:177], v[218:221], v[16:19]
	s_setprio 0
	s_barrier
	s_add_i32 s28, s28, s36
	v_lshl_add_u64 v[138:139], v[244:245], 0, s[86:87]
	s_mov_b32 m0, s28
	s_nop 0
	global_load_lds_dwordx4 v[138:139], off
	v_lshl_add_u64 v[138:139], v[246:247], 0, s[86:87]
	s_add_i32 m0, s28, 0x2000
	s_nop 0
	global_load_lds_dwordx4 v[138:139], off
	s_waitcnt vmcnt(6)
	s_barrier
	s_setprio 1
	v_mfma_f32_16x16x32_bf16 v[44:47], v[222:225], v[178:181], v[44:47]
	v_mfma_f32_16x16x32_bf16 v[40:43], v[230:233], v[178:181], v[40:43]
	v_mfma_f32_16x16x32_bf16 v[28:31], v[222:225], v[198:201], v[28:31]
	v_mfma_f32_16x16x32_bf16 v[24:27], v[230:233], v[198:201], v[24:27]
	v_mfma_f32_16x16x32_bf16 v[12:15], v[222:225], v[206:209], v[12:15]
	v_mfma_f32_16x16x32_bf16 v[8:11], v[230:233], v[206:209], v[8:11]
	v_mfma_f32_16x16x32_bf16 v[4:7], v[222:225], v[214:217], v[4:7]
	v_mfma_f32_16x16x32_bf16 v[0:3], v[230:233], v[214:217], v[0:3]
	v_mfma_f32_16x16x32_bf16 v[44:47], v[226:229], v[194:197], v[44:47]
	v_mfma_f32_16x16x32_bf16 v[40:43], v[234:237], v[194:197], v[40:43]
	v_mfma_f32_16x16x32_bf16 v[28:31], v[226:229], v[202:205], v[28:31]
	v_mfma_f32_16x16x32_bf16 v[24:27], v[234:237], v[202:205], v[24:27]
	v_mfma_f32_16x16x32_bf16 v[12:15], v[226:229], v[210:213], v[12:15]
	v_mfma_f32_16x16x32_bf16 v[8:11], v[234:237], v[210:213], v[8:11]
	v_mfma_f32_16x16x32_bf16 v[4:7], v[226:229], v[218:221], v[4:7]
	v_mfma_f32_16x16x32_bf16 v[0:3], v[234:237], v[218:221], v[0:3]
	s_setprio 0
	s_add_u32 s16, s16, 0x100
	s_addc_u32 s17, s17, 0
	s_add_u32 s75, s75, 0x100
	s_addc_u32 s82, s82, 0
	s_cmp_ge_u32 s83, s56
	s_mov_b32 s28, s83
	s_barrier
	s_cbranch_scc0 .LBB0_773
	s_ashr_i32 s16, s73, 31
	s_lshr_b32 s16, s16, 29
	s_add_i32 s16, s73, s16
	s_and_b32 s16, s16, 0xfffff8
	s_sub_i32 s16, s73, s16
	v_lshl_add_u32 v162, s74, 8, v140
	v_lshl_or_b32 v138, s16, 8, v142
	v_ashrrev_i32_e32 v139, 31, v138
	v_ashrrev_i32_e32 v163, 31, v162
	v_lshl_add_u64 v[164:165], v[138:139], 1, s[10:11]
	v_lshlrev_b64 v[138:139], 12, v[162:163]
	v_lshl_add_u64 v[138:139], v[164:165], 0, v[138:139]
	v_cvt_pk_bf16_f32 v60, v60, v61
	v_cvt_pk_bf16_f32 v61, v62, v63
	v_cvt_pk_bf16_f32 v62, v56, v57
	v_add_co_u32_e32 v56, vcc, s3, v138
	v_cvt_pk_bf16_f32 v68, v68, v69
	v_cvt_pk_bf16_f32 v69, v70, v71
	v_cvt_pk_bf16_f32 v70, v64, v65
	v_lshl_add_u64 v[64:65], v[138:139], 0, s[84:85]
	s_nop 0
	v_addc_co_u32_e32 v57, vcc, 0, v139, vcc
	v_cvt_pk_bf16_f32 v44, v44, v45
	v_cvt_pk_bf16_f32 v45, v46, v47
	v_cvt_pk_bf16_f32 v46, v40, v41
	v_cvt_pk_bf16_f32 v47, v42, v43
	global_store_dwordx4 v[64:65], v[44:47], off offset:256
	v_cvt_pk_bf16_f32 v112, v112, v113
	v_cvt_pk_bf16_f32 v113, v114, v115
	v_cvt_pk_bf16_f32 v114, v104, v105
	v_or_b32_e32 v104, 16, v162
	v_cvt_pk_bf16_f32 v28, v28, v29
	s_nop 0
	v_add_co_u32_e32 v46, vcc, s93, v138
	v_lshl_add_u64 v[44:45], v[138:139], 0, s[46:47]
	s_nop 0
	v_addc_co_u32_e32 v47, vcc, 0, v139, vcc
	v_cvt_pk_bf16_f32 v29, v30, v31
	v_cvt_pk_bf16_f32 v30, v24, v25
	v_ashrrev_i32_e32 v105, 31, v104
	v_cvt_pk_bf16_f32 v96, v96, v97
	v_cvt_pk_bf16_f32 v97, v98, v99
	v_cvt_pk_bf16_f32 v98, v88, v89
	v_or_b32_e32 v88, 32, v162
	v_cvt_pk_bf16_f32 v31, v26, v27
	global_store_dwordx4 v[44:45], v[28:31], off offset:256
	v_lshlrev_b64 v[104:105], 12, v[104:105]
	v_ashrrev_i32_e32 v89, 31, v88
	v_add_co_u32_e32 v30, vcc, s97, v138
	v_cvt_pk_bf16_f32 v80, v80, v81
	v_cvt_pk_bf16_f32 v81, v82, v83
	v_cvt_pk_bf16_f32 v82, v72, v73
	v_or_b32_e32 v72, 48, v162
	v_lshl_add_u64 v[28:29], v[138:139], 0, s[42:43]
	v_addc_co_u32_e32 v31, vcc, 0, v139, vcc
	v_cvt_pk_bf16_f32 v12, v12, v13
	v_cvt_pk_bf16_f32 v13, v14, v15
	v_cvt_pk_bf16_f32 v14, v8, v9
	v_cvt_pk_bf16_f32 v115, v106, v107
	global_store_dwordx4 v[138:139], v[112:115], off offset:256
	v_lshlrev_b64 v[88:89], 12, v[88:89]
	v_ashrrev_i32_e32 v73, 31, v72
	v_lshl_add_u64 v[112:113], v[164:165], 0, v[104:105]
	v_cvt_pk_bf16_f32 v15, v10, v11
	global_store_dwordx4 v[28:29], v[12:15], off offset:256
	v_cvt_pk_bf16_f32 v99, v90, v91
	global_store_dwordx4 v[112:113], v[96:99], off offset:256
	v_lshlrev_b64 v[72:73], 12, v[72:73]
	v_add_co_u32_e32 v14, vcc, s91, v138
	v_lshl_add_u64 v[96:97], v[164:165], 0, v[88:89]
	s_nop 0
	v_addc_co_u32_e32 v15, vcc, 0, v139, vcc
	v_cvt_pk_bf16_f32 v83, v74, v75
	global_store_dwordx4 v[96:97], v[80:83], off offset:256
	v_lshl_add_u64 v[12:13], v[138:139], 0, s[62:63]
	s_and_b64 vcc, exec, s[4:5]
	v_lshl_add_u64 v[80:81], v[164:165], 0, v[72:73]
	s_mov_b32 s73, s71
	s_mov_b32 s74, s72
	s_mov_b64 s[28:29], s[8:9]
	s_mov_b64 s[16:17], s[6:7]
	v_cvt_pk_bf16_f32 v124, v124, v125
	v_cvt_pk_bf16_f32 v125, v126, v127
	v_cvt_pk_bf16_f32 v126, v120, v121
	v_cvt_pk_bf16_f32 v127, v122, v123
	global_store_dwordx4 v[138:139], v[124:127], off
	v_cvt_pk_bf16_f32 v104, v116, v117
	v_cvt_pk_bf16_f32 v105, v118, v119
	v_cvt_pk_bf16_f32 v106, v108, v109
	v_cvt_pk_bf16_f32 v107, v110, v111
	global_store_dwordx4 v[112:113], v[104:107], off
	v_cvt_pk_bf16_f32 v88, v100, v101
	v_cvt_pk_bf16_f32 v89, v102, v103
	v_cvt_pk_bf16_f32 v90, v92, v93
	v_cvt_pk_bf16_f32 v91, v94, v95
	global_store_dwordx4 v[96:97], v[88:91], off
	v_cvt_pk_bf16_f32 v72, v84, v85
	v_cvt_pk_bf16_f32 v73, v86, v87
	v_cvt_pk_bf16_f32 v74, v76, v77
	v_cvt_pk_bf16_f32 v75, v78, v79
	global_store_dwordx4 v[80:81], v[72:75], off
	v_cvt_pk_bf16_f32 v71, v66, v67
	global_store_dwordx4 v[80:81], v[68:71], off offset:256
	v_cvt_pk_bf16_f32 v63, v58, v59
	global_store_dwordx4 v[56:57], v[60:63], off
	v_cvt_pk_bf16_f32 v40, v52, v53
	v_cvt_pk_bf16_f32 v41, v54, v55
	v_cvt_pk_bf16_f32 v42, v48, v49
	v_cvt_pk_bf16_f32 v43, v50, v51
	global_store_dwordx4 v[46:47], v[40:43], off
	v_cvt_pk_bf16_f32 v24, v36, v37
	v_cvt_pk_bf16_f32 v25, v38, v39
	v_cvt_pk_bf16_f32 v26, v32, v33
	v_cvt_pk_bf16_f32 v27, v34, v35
	global_store_dwordx4 v[30:31], v[24:27], off
	v_cvt_pk_bf16_f32 v8, v20, v21
	v_cvt_pk_bf16_f32 v9, v22, v23
	v_cvt_pk_bf16_f32 v10, v16, v17
	v_cvt_pk_bf16_f32 v11, v18, v19
	global_store_dwordx4 v[14:15], v[8:11], off
	v_cvt_pk_bf16_f32 v4, v4, v5
	v_cvt_pk_bf16_f32 v5, v6, v7
	v_cvt_pk_bf16_f32 v6, v0, v1
	v_cvt_pk_bf16_f32 v7, v2, v3
	global_store_dwordx4 v[12:13], v[4:7], off offset:256
	s_cbranch_vccz .LBB0_762
	s_waitcnt vmcnt(0)
	s_cmpk_gt_u32 s13, 0xff
	s_mov_b32 s55, 0xbc00000
	s_cbranch_scc1 .LBB0_777
	s_barrier
